# conformer pointwise matmul: 24 A-fragment LDS reads issued ahead into fresh registers (counted waits); tile_out of all three mixer parts: reads batched ahead of the write-through stores
# baseline (speedup 1.0000x reference)
.LBB0_593:
	s_or_b64 exec, exec, s[26:27]
	s_ashr_i32 s27, s66, 6
	s_lshl_b32 s26, s27, 5
	v_and_b32_e32 v158, 15, v156
	s_add_i32 s23, s26, s24
	v_or_b32_e32 v0, s23, v158
	v_ashrrev_i32_e32 v1, 31, v0
	v_readlane_b32 s42, v254, 56
	v_lshlrev_b64 v[0:1], 9, v[0:1]
	v_readlane_b32 s43, v254, 57
	v_and_b32_e32 v148, 48, v156
	v_ashrrev_i32_e32 v166, 3, v156
	v_lshl_add_u64 v[0:1], s[42:43], 0, v[0:1]
	v_lshl_add_u64 v[0:1], v[0:1], 0, v[148:149]
	v_and_b32_e32 v159, -16, v166
	v_lshl_add_u32 v167, v157, 2, 0
	v_add_co_u32_e32 v2, vcc, 0x2000, v0
	v_lshl_add_u32 v161, v159, 9, v167
	s_nop 0
	v_addc_co_u32_e32 v3, vcc, 0, v1, vcc
	global_load_dwordx4 v[56:59], v[0:1], off
	global_load_dwordx4 v[48:51], v[0:1], off offset:64
	global_load_dwordx4 v[60:63], v[2:3], off
	global_load_dwordx4 v[52:55], v[2:3], off offset:64
	global_load_dwordx4 v[40:43], v[0:1], off offset:128
	global_load_dwordx4 v[32:35], v[0:1], off offset:192
	global_load_dwordx4 v[44:47], v[2:3], off offset:128
	global_load_dwordx4 v[36:39], v[2:3], off offset:192
	global_load_dwordx4 v[24:27], v[0:1], off offset:256
	global_load_dwordx4 v[16:19], v[0:1], off offset:320
	global_load_dwordx4 v[28:31], v[2:3], off offset:256
	global_load_dwordx4 v[20:23], v[2:3], off offset:320
	v_mov_b32_e32 v248, v161
	ds_read_b32 v244, v248
	ds_read_b32 v245, v248 offset:512
	ds_read_b32 v246, v248 offset:1024
	ds_read_b32 v247, v248 offset:1536
	v_or_b32_e32 v160, 1, v159
	v_mov_b64_e32 v[164:165], v[126:127]
	v_mov_b64_e32 v[168:169], v[126:127]
	v_mov_b64_e32 v[170:171], v[126:127]
	s_waitcnt lgkmcnt(3)
	v_mov_b32_e32 v129, v244
	v_lshlrev_b32_e32 v128, 16, v129
	v_and_b32_e32 v129, 0xffff0000, v129
	v_pk_fma_f32 v[162:163], v[124:125], v[128:129], v[126:127]
	v_mov_b64_e32 v[172:173], v[126:127]
	v_mov_b64_e32 v[174:175], v[126:127]
	v_mov_b64_e32 v[144:145], v[126:127]
	v_mov_b64_e32 v[142:143], v[126:127]
	v_mov_b64_e32 v[140:141], v[126:127]
	v_mov_b64_e32 v[138:139], v[126:127]
	v_mov_b64_e32 v[136:137], v[126:127]
	v_mov_b64_e32 v[134:135], v[126:127]
	v_mov_b64_e32 v[132:133], v[126:127]
	v_mov_b64_e32 v[130:131], v[126:127]
	v_mov_b64_e32 v[128:129], v[126:127]
	v_lshl_add_u32 v154, v160, 9, v167
	global_load_dwordx4 v[8:11], v[0:1], off offset:384
	global_load_dwordx4 v[4:7], v[0:1], off offset:448
	global_load_dwordx4 v[12:15], v[2:3], off offset:384
	s_nop 0
	global_load_dwordx4 v[0:3], v[2:3], off offset:448
	ds_read_b32 v244, v248 offset:2048
	v_readlane_b32 s42, v255, 5
	v_readlane_b32 s43, v255, 6
	s_lshl_b32 s23, s27, 13
	s_add_i32 s23, s23, 0
	s_waitcnt lgkmcnt(3)
	v_mov_b32_e32 v154, v245
	v_lshlrev_b32_e32 v176, 16, v154
	v_and_b32_e32 v177, 0xffff0000, v154
	v_pk_fma_f32 v[162:163], v[122:123], v[176:177], v[162:163]
	v_pk_fma_f32 v[176:177], v[124:125], v[176:177], v[126:127]
	v_or_b32_e32 v126, 2, v159
	v_lshl_add_u32 v127, v126, 9, v167
	ds_read_b32 v245, v248 offset:2560
	s_mov_b32 s46, 0x3b800000
	s_waitcnt lgkmcnt(3)
	v_mov_b32_e32 v127, v246
	v_lshlrev_b32_e32 v178, 16, v127
	v_and_b32_e32 v179, 0xffff0000, v127
	v_or_b32_e32 v127, 3, v159
	v_pk_fma_f32 v[162:163], v[120:121], v[178:179], v[162:163]
	v_pk_fma_f32 v[176:177], v[122:123], v[178:179], v[176:177]
	v_pk_fma_f32 v[164:165], v[124:125], v[178:179], v[164:165]
	v_lshl_add_u32 v154, v127, 9, v167
	ds_read_b32 v246, v248 offset:3072
	s_waitcnt lgkmcnt(3)
	v_mov_b32_e32 v154, v247
	v_lshlrev_b32_e32 v178, 16, v154
	v_and_b32_e32 v179, 0xffff0000, v154
	v_pk_fma_f32 v[180:181], v[118:119], v[178:179], v[162:163]
	v_or_b32_e32 v162, 4, v159
	v_pk_fma_f32 v[176:177], v[120:121], v[178:179], v[176:177]
	v_pk_fma_f32 v[164:165], v[122:123], v[178:179], v[164:165]
	v_pk_fma_f32 v[168:169], v[124:125], v[178:179], v[168:169]
	v_lshl_add_u32 v154, v162, 9, v167
	ds_read_b32 v247, v248 offset:3584
	v_or_b32_e32 v163, 5, v159
	s_waitcnt lgkmcnt(3)
	v_mov_b32_e32 v154, v244
	v_lshlrev_b32_e32 v178, 16, v154
	v_and_b32_e32 v179, 0xffff0000, v154
	v_pk_fma_f32 v[180:181], v[116:117], v[178:179], v[180:181]
	v_pk_fma_f32 v[176:177], v[118:119], v[178:179], v[176:177]
	v_pk_fma_f32 v[164:165], v[120:121], v[178:179], v[164:165]
	v_pk_fma_f32 v[168:169], v[122:123], v[178:179], v[168:169]
	v_pk_fma_f32 v[170:171], v[124:125], v[178:179], v[170:171]
	v_lshl_add_u32 v154, v163, 9, v167
	ds_read_b32 v244, v248 offset:4096
	s_waitcnt lgkmcnt(3)
	v_mov_b32_e32 v154, v245
	v_lshlrev_b32_e32 v178, 16, v154
	v_and_b32_e32 v179, 0xffff0000, v154
	v_pk_fma_f32 v[182:183], v[118:119], v[178:179], v[164:165]
	v_or_b32_e32 v164, 6, v159
	v_pk_fma_f32 v[180:181], v[114:115], v[178:179], v[180:181]
	v_pk_fma_f32 v[176:177], v[116:117], v[178:179], v[176:177]
	v_pk_fma_f32 v[168:169], v[120:121], v[178:179], v[168:169]
	v_pk_fma_f32 v[170:171], v[122:123], v[178:179], v[170:171]
	v_pk_fma_f32 v[172:173], v[124:125], v[178:179], v[172:173]
	v_lshl_add_u32 v154, v164, 9, v167
	ds_read_b32 v245, v248 offset:4608
	v_or_b32_e32 v165, 7, v159
	s_waitcnt lgkmcnt(3)
	v_mov_b32_e32 v154, v246
	v_lshlrev_b32_e32 v178, 16, v154
	v_and_b32_e32 v179, 0xffff0000, v154
	v_pk_fma_f32 v[180:181], v[112:113], v[178:179], v[180:181]
	v_pk_fma_f32 v[176:177], v[114:115], v[178:179], v[176:177]
	v_pk_fma_f32 v[182:183], v[116:117], v[178:179], v[182:183]
	v_pk_fma_f32 v[168:169], v[118:119], v[178:179], v[168:169]
	v_pk_fma_f32 v[170:171], v[120:121], v[178:179], v[170:171]
	v_pk_fma_f32 v[172:173], v[122:123], v[178:179], v[172:173]
	v_pk_fma_f32 v[174:175], v[124:125], v[178:179], v[174:175]
	v_lshl_add_u32 v154, v165, 9, v167
	ds_read_b32 v246, v248 offset:5120
	s_waitcnt lgkmcnt(3)
	v_mov_b32_e32 v154, v247
	v_lshlrev_b32_e32 v178, 16, v154
	v_and_b32_e32 v179, 0xffff0000, v154
	v_pk_fma_f32 v[180:181], v[110:111], v[178:179], v[180:181]
	v_pk_fma_f32 v[176:177], v[112:113], v[178:179], v[176:177]
	v_pk_fma_f32 v[182:183], v[114:115], v[178:179], v[182:183]
	v_pk_fma_f32 v[168:169], v[116:117], v[178:179], v[168:169]
	v_pk_fma_f32 v[170:171], v[118:119], v[178:179], v[170:171]
	v_pk_fma_f32 v[172:173], v[120:121], v[178:179], v[172:173]
	v_pk_fma_f32 v[174:175], v[122:123], v[178:179], v[174:175]
	v_pk_fma_f32 v[178:179], v[124:125], v[178:179], v[144:145]
	v_or_b32_e32 v144, 8, v159
	v_lshl_add_u32 v145, v144, 9, v167
	ds_read_b32 v247, v248 offset:5632
	s_waitcnt lgkmcnt(3)
	v_mov_b32_e32 v145, v244
	v_lshlrev_b32_e32 v184, 16, v145
	v_and_b32_e32 v185, 0xffff0000, v145
	v_pk_fma_f32 v[180:181], v[108:109], v[184:185], v[180:181]
	v_pk_fma_f32 v[176:177], v[110:111], v[184:185], v[176:177]
	v_pk_fma_f32 v[182:183], v[112:113], v[184:185], v[182:183]
	v_pk_fma_f32 v[168:169], v[114:115], v[184:185], v[168:169]
	v_pk_fma_f32 v[170:171], v[116:117], v[184:185], v[170:171]
	v_pk_fma_f32 v[172:173], v[118:119], v[184:185], v[172:173]
	v_pk_fma_f32 v[174:175], v[120:121], v[184:185], v[174:175]
	v_pk_fma_f32 v[178:179], v[122:123], v[184:185], v[178:179]
	v_pk_fma_f32 v[184:185], v[124:125], v[184:185], v[142:143]
	v_or_b32_e32 v142, 9, v159
	v_lshl_add_u32 v143, v142, 9, v167
	ds_read_b32 v244, v248 offset:6144
	s_waitcnt lgkmcnt(3)
	v_mov_b32_e32 v143, v245
	v_lshlrev_b32_e32 v186, 16, v143
	v_and_b32_e32 v187, 0xffff0000, v143
	v_pk_fma_f32 v[180:181], v[106:107], v[186:187], v[180:181]
	v_pk_fma_f32 v[176:177], v[108:109], v[186:187], v[176:177]
	v_pk_fma_f32 v[182:183], v[110:111], v[186:187], v[182:183]
	v_pk_fma_f32 v[168:169], v[112:113], v[186:187], v[168:169]
	v_pk_fma_f32 v[170:171], v[114:115], v[186:187], v[170:171]
	v_pk_fma_f32 v[172:173], v[116:117], v[186:187], v[172:173]
	v_pk_fma_f32 v[174:175], v[118:119], v[186:187], v[174:175]
	v_pk_fma_f32 v[178:179], v[120:121], v[186:187], v[178:179]
	v_pk_fma_f32 v[184:185], v[122:123], v[186:187], v[184:185]
	v_pk_fma_f32 v[186:187], v[124:125], v[186:187], v[140:141]
	v_or_b32_e32 v140, 10, v159
	v_lshl_add_u32 v141, v140, 9, v167
	ds_read_b32 v245, v248 offset:6656
	s_waitcnt lgkmcnt(3)
	v_mov_b32_e32 v141, v246
	v_lshlrev_b32_e32 v188, 16, v141
	v_and_b32_e32 v189, 0xffff0000, v141
	v_pk_fma_f32 v[180:181], v[104:105], v[188:189], v[180:181]
	v_pk_fma_f32 v[176:177], v[106:107], v[188:189], v[176:177]
	v_pk_fma_f32 v[182:183], v[108:109], v[188:189], v[182:183]
	v_pk_fma_f32 v[168:169], v[110:111], v[188:189], v[168:169]
	v_pk_fma_f32 v[170:171], v[112:113], v[188:189], v[170:171]
	v_pk_fma_f32 v[172:173], v[114:115], v[188:189], v[172:173]
	v_pk_fma_f32 v[174:175], v[116:117], v[188:189], v[174:175]
	v_pk_fma_f32 v[178:179], v[118:119], v[188:189], v[178:179]
	v_pk_fma_f32 v[184:185], v[120:121], v[188:189], v[184:185]
	v_pk_fma_f32 v[186:187], v[122:123], v[188:189], v[186:187]
	v_pk_fma_f32 v[188:189], v[124:125], v[188:189], v[138:139]
	v_or_b32_e32 v138, 11, v159
	v_lshl_add_u32 v139, v138, 9, v167
	ds_read_b32 v246, v248 offset:7168
	s_waitcnt lgkmcnt(3)
	v_mov_b32_e32 v139, v247
	v_lshlrev_b32_e32 v190, 16, v139
	v_and_b32_e32 v191, 0xffff0000, v139
	v_pk_fma_f32 v[180:181], v[102:103], v[190:191], v[180:181]
	v_pk_fma_f32 v[176:177], v[104:105], v[190:191], v[176:177]
	v_pk_fma_f32 v[182:183], v[106:107], v[190:191], v[182:183]
	v_pk_fma_f32 v[168:169], v[108:109], v[190:191], v[168:169]
	v_pk_fma_f32 v[170:171], v[110:111], v[190:191], v[170:171]
	v_pk_fma_f32 v[172:173], v[112:113], v[190:191], v[172:173]
	v_pk_fma_f32 v[174:175], v[114:115], v[190:191], v[174:175]
	v_pk_fma_f32 v[178:179], v[116:117], v[190:191], v[178:179]
	v_pk_fma_f32 v[184:185], v[118:119], v[190:191], v[184:185]
	v_pk_fma_f32 v[186:187], v[120:121], v[190:191], v[186:187]
	v_pk_fma_f32 v[188:189], v[122:123], v[190:191], v[188:189]
	v_pk_fma_f32 v[190:191], v[124:125], v[190:191], v[136:137]
	v_or_b32_e32 v136, 12, v159
	v_lshl_add_u32 v137, v136, 9, v167
	ds_read_b32 v247, v248 offset:7680
	s_waitcnt lgkmcnt(3)
	v_mov_b32_e32 v137, v244
	v_lshlrev_b32_e32 v192, 16, v137
	v_and_b32_e32 v193, 0xffff0000, v137
	v_pk_fma_f32 v[180:181], v[100:101], v[192:193], v[180:181]
	v_pk_fma_f32 v[176:177], v[102:103], v[192:193], v[176:177]
	v_pk_fma_f32 v[182:183], v[104:105], v[192:193], v[182:183]
	v_pk_fma_f32 v[168:169], v[106:107], v[192:193], v[168:169]
	v_pk_fma_f32 v[170:171], v[108:109], v[192:193], v[170:171]
	v_pk_fma_f32 v[172:173], v[110:111], v[192:193], v[172:173]
	v_pk_fma_f32 v[174:175], v[112:113], v[192:193], v[174:175]
	v_pk_fma_f32 v[178:179], v[114:115], v[192:193], v[178:179]
	v_pk_fma_f32 v[184:185], v[116:117], v[192:193], v[184:185]
	v_pk_fma_f32 v[186:187], v[118:119], v[192:193], v[186:187]
	v_pk_fma_f32 v[188:189], v[120:121], v[192:193], v[188:189]
	v_pk_fma_f32 v[190:191], v[122:123], v[192:193], v[190:191]
	v_pk_fma_f32 v[192:193], v[124:125], v[192:193], v[134:135]
	v_or_b32_e32 v134, 13, v159
	v_lshl_add_u32 v135, v134, 9, v167
	ds_read_b32 v244, v248 offset:8192
	s_waitcnt lgkmcnt(3)
	v_mov_b32_e32 v135, v245
	v_lshlrev_b32_e32 v194, 16, v135
	v_and_b32_e32 v195, 0xffff0000, v135
	v_pk_fma_f32 v[180:181], v[98:99], v[194:195], v[180:181]
	v_pk_fma_f32 v[176:177], v[100:101], v[194:195], v[176:177]
	v_pk_fma_f32 v[182:183], v[102:103], v[194:195], v[182:183]
	v_pk_fma_f32 v[168:169], v[104:105], v[194:195], v[168:169]
	v_pk_fma_f32 v[170:171], v[106:107], v[194:195], v[170:171]
	v_pk_fma_f32 v[172:173], v[108:109], v[194:195], v[172:173]
	v_pk_fma_f32 v[174:175], v[110:111], v[194:195], v[174:175]
	v_pk_fma_f32 v[178:179], v[112:113], v[194:195], v[178:179]
	v_pk_fma_f32 v[184:185], v[114:115], v[194:195], v[184:185]
	v_pk_fma_f32 v[186:187], v[116:117], v[194:195], v[186:187]
	v_pk_fma_f32 v[188:189], v[118:119], v[194:195], v[188:189]
	v_pk_fma_f32 v[190:191], v[120:121], v[194:195], v[190:191]
	v_pk_fma_f32 v[192:193], v[122:123], v[194:195], v[192:193]
	v_pk_fma_f32 v[194:195], v[124:125], v[194:195], v[132:133]
	v_or_b32_e32 v132, 14, v159
	v_lshl_add_u32 v133, v132, 9, v167
	ds_read_b32 v245, v248 offset:8704
	s_waitcnt lgkmcnt(3)
	v_mov_b32_e32 v133, v246
	v_lshlrev_b32_e32 v196, 16, v133
	v_and_b32_e32 v197, 0xffff0000, v133
	v_pk_fma_f32 v[180:181], v[96:97], v[196:197], v[180:181]
	v_pk_fma_f32 v[176:177], v[98:99], v[196:197], v[176:177]
	v_pk_fma_f32 v[182:183], v[100:101], v[196:197], v[182:183]
	v_pk_fma_f32 v[168:169], v[102:103], v[196:197], v[168:169]
	v_pk_fma_f32 v[170:171], v[104:105], v[196:197], v[170:171]
	v_pk_fma_f32 v[172:173], v[106:107], v[196:197], v[172:173]
	v_pk_fma_f32 v[174:175], v[108:109], v[196:197], v[174:175]
	v_pk_fma_f32 v[178:179], v[110:111], v[196:197], v[178:179]
	v_pk_fma_f32 v[184:185], v[112:113], v[196:197], v[184:185]
	v_pk_fma_f32 v[186:187], v[114:115], v[196:197], v[186:187]
	v_pk_fma_f32 v[188:189], v[116:117], v[196:197], v[188:189]
	v_pk_fma_f32 v[190:191], v[118:119], v[196:197], v[190:191]
	v_pk_fma_f32 v[192:193], v[120:121], v[196:197], v[192:193]
	v_pk_fma_f32 v[194:195], v[122:123], v[196:197], v[194:195]
	v_pk_fma_f32 v[196:197], v[124:125], v[196:197], v[130:131]
	v_or_b32_e32 v130, 15, v166
	v_lshl_add_u32 v131, v130, 9, v167
	ds_read_b32 v246, v248 offset:9216
	s_waitcnt lgkmcnt(3)
	v_mov_b32_e32 v131, v247
	v_lshlrev_b32_e32 v166, 16, v131
	v_and_b32_e32 v167, 0xffff0000, v131
	v_pk_fma_f32 v[180:181], v[94:95], v[166:167], v[180:181]
	v_pk_fma_f32 v[176:177], v[96:97], v[166:167], v[176:177]
	v_pk_fma_f32 v[182:183], v[98:99], v[166:167], v[182:183]
	v_pk_fma_f32 v[168:169], v[100:101], v[166:167], v[168:169]
	v_pk_fma_f32 v[170:171], v[102:103], v[166:167], v[170:171]
	v_pk_fma_f32 v[172:173], v[104:105], v[166:167], v[172:173]
	v_pk_fma_f32 v[174:175], v[106:107], v[166:167], v[174:175]
	v_pk_fma_f32 v[178:179], v[108:109], v[166:167], v[178:179]
	v_pk_fma_f32 v[184:185], v[110:111], v[166:167], v[184:185]
	v_pk_fma_f32 v[186:187], v[112:113], v[166:167], v[186:187]
	v_pk_fma_f32 v[188:189], v[114:115], v[166:167], v[188:189]
	v_pk_fma_f32 v[190:191], v[116:117], v[166:167], v[190:191]
	v_pk_fma_f32 v[192:193], v[118:119], v[166:167], v[192:193]
	v_pk_fma_f32 v[194:195], v[120:121], v[166:167], v[194:195]
	v_pk_fma_f32 v[196:197], v[122:123], v[166:167], v[196:197]
	v_pk_fma_f32 v[124:125], v[124:125], v[166:167], v[128:129]
	s_nop 0
	ds_read_b32 v247, v248 offset:9728
	s_waitcnt lgkmcnt(3)
	v_mov_b32_e32 v129, v244
	v_lshlrev_b32_e32 v128, 16, v129
	v_and_b32_e32 v129, 0xffff0000, v129
	v_pk_fma_f32 v[166:167], v[92:93], v[128:129], v[180:181]
	v_pk_fma_f32 v[176:177], v[94:95], v[128:129], v[176:177]
	v_pk_fma_f32 v[180:181], v[96:97], v[128:129], v[182:183]
	v_pk_fma_f32 v[168:169], v[98:99], v[128:129], v[168:169]
	v_pk_fma_f32 v[170:171], v[100:101], v[128:129], v[170:171]
	v_pk_fma_f32 v[172:173], v[102:103], v[128:129], v[172:173]
	v_pk_fma_f32 v[174:175], v[104:105], v[128:129], v[174:175]
	v_pk_fma_f32 v[178:179], v[106:107], v[128:129], v[178:179]
	v_pk_fma_f32 v[182:183], v[108:109], v[128:129], v[184:185]
	v_pk_fma_f32 v[184:185], v[110:111], v[128:129], v[186:187]
	v_pk_fma_f32 v[186:187], v[112:113], v[128:129], v[188:189]
	v_pk_fma_f32 v[188:189], v[114:115], v[128:129], v[190:191]
	v_pk_fma_f32 v[190:191], v[116:117], v[128:129], v[192:193]
	v_pk_fma_f32 v[192:193], v[118:119], v[128:129], v[194:195]
	v_pk_fma_f32 v[194:195], v[120:121], v[128:129], v[196:197]
	v_pk_fma_f32 v[122:123], v[122:123], v[128:129], v[124:125]
	s_nop 0
	ds_read_b32 v244, v248 offset:10240
	s_waitcnt lgkmcnt(3)
	v_mov_b32_e32 v125, v245
	v_lshlrev_b32_e32 v124, 16, v125
	v_and_b32_e32 v125, 0xffff0000, v125
	v_pk_fma_f32 v[128:129], v[90:91], v[124:125], v[166:167]
	v_pk_fma_f32 v[166:167], v[92:93], v[124:125], v[176:177]
	v_pk_fma_f32 v[176:177], v[94:95], v[124:125], v[180:181]
	v_pk_fma_f32 v[168:169], v[96:97], v[124:125], v[168:169]
	v_pk_fma_f32 v[170:171], v[98:99], v[124:125], v[170:171]
	v_pk_fma_f32 v[172:173], v[100:101], v[124:125], v[172:173]
	v_pk_fma_f32 v[174:175], v[102:103], v[124:125], v[174:175]
	v_pk_fma_f32 v[178:179], v[104:105], v[124:125], v[178:179]
	v_pk_fma_f32 v[180:181], v[106:107], v[124:125], v[182:183]
	v_pk_fma_f32 v[182:183], v[108:109], v[124:125], v[184:185]
	v_pk_fma_f32 v[184:185], v[110:111], v[124:125], v[186:187]
	v_pk_fma_f32 v[186:187], v[112:113], v[124:125], v[188:189]
	v_pk_fma_f32 v[188:189], v[114:115], v[124:125], v[190:191]
	v_pk_fma_f32 v[190:191], v[116:117], v[124:125], v[192:193]
	v_pk_fma_f32 v[192:193], v[118:119], v[124:125], v[194:195]
	v_pk_fma_f32 v[120:121], v[120:121], v[124:125], v[122:123]
	s_nop 0
	ds_read_b32 v245, v248 offset:10752
	s_waitcnt lgkmcnt(3)
	v_mov_b32_e32 v123, v246
	v_lshlrev_b32_e32 v122, 16, v123
	v_and_b32_e32 v123, 0xffff0000, v123
	v_pk_fma_f32 v[124:125], v[88:89], v[122:123], v[128:129]
	v_pk_fma_f32 v[128:129], v[90:91], v[122:123], v[166:167]
	v_pk_fma_f32 v[166:167], v[92:93], v[122:123], v[176:177]
	v_pk_fma_f32 v[168:169], v[94:95], v[122:123], v[168:169]
	v_pk_fma_f32 v[170:171], v[96:97], v[122:123], v[170:171]
	v_pk_fma_f32 v[172:173], v[98:99], v[122:123], v[172:173]
	v_pk_fma_f32 v[174:175], v[100:101], v[122:123], v[174:175]
	v_pk_fma_f32 v[176:177], v[102:103], v[122:123], v[178:179]
	v_pk_fma_f32 v[178:179], v[104:105], v[122:123], v[180:181]
	v_pk_fma_f32 v[180:181], v[106:107], v[122:123], v[182:183]
	v_pk_fma_f32 v[182:183], v[108:109], v[122:123], v[184:185]
	v_pk_fma_f32 v[184:185], v[110:111], v[122:123], v[186:187]
	v_pk_fma_f32 v[186:187], v[112:113], v[122:123], v[188:189]
	v_pk_fma_f32 v[188:189], v[114:115], v[122:123], v[190:191]
	v_pk_fma_f32 v[190:191], v[116:117], v[122:123], v[192:193]
	v_pk_fma_f32 v[118:119], v[118:119], v[122:123], v[120:121]
	s_nop 0
	ds_read_b32 v246, v248 offset:11264
	s_waitcnt lgkmcnt(3)
	v_mov_b32_e32 v121, v247
	v_lshlrev_b32_e32 v120, 16, v121
	v_and_b32_e32 v121, 0xffff0000, v121
	v_pk_fma_f32 v[122:123], v[86:87], v[120:121], v[124:125]
	v_pk_fma_f32 v[124:125], v[88:89], v[120:121], v[128:129]
	v_pk_fma_f32 v[128:129], v[90:91], v[120:121], v[166:167]
	v_pk_fma_f32 v[166:167], v[92:93], v[120:121], v[168:169]
	v_pk_fma_f32 v[168:169], v[94:95], v[120:121], v[170:171]
	v_pk_fma_f32 v[170:171], v[96:97], v[120:121], v[172:173]
	v_pk_fma_f32 v[172:173], v[98:99], v[120:121], v[174:175]
	v_pk_fma_f32 v[174:175], v[100:101], v[120:121], v[176:177]
	v_pk_fma_f32 v[176:177], v[102:103], v[120:121], v[178:179]
	v_pk_fma_f32 v[178:179], v[104:105], v[120:121], v[180:181]
	v_pk_fma_f32 v[180:181], v[106:107], v[120:121], v[182:183]
	v_pk_fma_f32 v[182:183], v[108:109], v[120:121], v[184:185]
	v_pk_fma_f32 v[184:185], v[110:111], v[120:121], v[186:187]
	v_pk_fma_f32 v[186:187], v[112:113], v[120:121], v[188:189]
	v_pk_fma_f32 v[188:189], v[114:115], v[120:121], v[190:191]
	v_pk_fma_f32 v[116:117], v[116:117], v[120:121], v[118:119]
	s_nop 0
	ds_read_b32 v247, v248 offset:11776
	s_waitcnt lgkmcnt(3)
	v_mov_b32_e32 v119, v244
	v_lshlrev_b32_e32 v118, 16, v119
	v_and_b32_e32 v119, 0xffff0000, v119
	v_pk_fma_f32 v[120:121], v[84:85], v[118:119], v[122:123]
	v_pk_fma_f32 v[122:123], v[86:87], v[118:119], v[124:125]
	v_pk_fma_f32 v[124:125], v[88:89], v[118:119], v[128:129]
	v_pk_fma_f32 v[128:129], v[90:91], v[118:119], v[166:167]
	v_pk_fma_f32 v[166:167], v[92:93], v[118:119], v[168:169]
	v_pk_fma_f32 v[168:169], v[94:95], v[118:119], v[170:171]
	v_pk_fma_f32 v[170:171], v[96:97], v[118:119], v[172:173]
	v_pk_fma_f32 v[172:173], v[98:99], v[118:119], v[174:175]
	v_pk_fma_f32 v[174:175], v[100:101], v[118:119], v[176:177]
	v_pk_fma_f32 v[176:177], v[102:103], v[118:119], v[178:179]
	v_pk_fma_f32 v[178:179], v[104:105], v[118:119], v[180:181]
	v_pk_fma_f32 v[180:181], v[106:107], v[118:119], v[182:183]
	v_pk_fma_f32 v[182:183], v[108:109], v[118:119], v[184:185]
	v_pk_fma_f32 v[184:185], v[110:111], v[118:119], v[186:187]
	v_pk_fma_f32 v[186:187], v[112:113], v[118:119], v[188:189]
	v_pk_fma_f32 v[114:115], v[114:115], v[118:119], v[116:117]
	s_nop 0
	ds_read_b32 v244, v248 offset:12288
	s_waitcnt lgkmcnt(3)
	v_mov_b32_e32 v117, v245
	v_lshlrev_b32_e32 v116, 16, v117
	v_and_b32_e32 v117, 0xffff0000, v117
	v_pk_fma_f32 v[118:119], v[82:83], v[116:117], v[120:121]
	v_pk_fma_f32 v[120:121], v[84:85], v[116:117], v[122:123]
	v_pk_fma_f32 v[122:123], v[86:87], v[116:117], v[124:125]
	v_pk_fma_f32 v[124:125], v[88:89], v[116:117], v[128:129]
	v_pk_fma_f32 v[128:129], v[90:91], v[116:117], v[166:167]
	v_pk_fma_f32 v[166:167], v[92:93], v[116:117], v[168:169]
	v_pk_fma_f32 v[168:169], v[94:95], v[116:117], v[170:171]
	v_pk_fma_f32 v[170:171], v[96:97], v[116:117], v[172:173]
	v_pk_fma_f32 v[172:173], v[98:99], v[116:117], v[174:175]
	v_pk_fma_f32 v[174:175], v[100:101], v[116:117], v[176:177]
	v_pk_fma_f32 v[176:177], v[102:103], v[116:117], v[178:179]
	v_pk_fma_f32 v[178:179], v[104:105], v[116:117], v[180:181]
	v_pk_fma_f32 v[180:181], v[106:107], v[116:117], v[182:183]
	v_pk_fma_f32 v[182:183], v[108:109], v[116:117], v[184:185]
	v_pk_fma_f32 v[184:185], v[110:111], v[116:117], v[186:187]
	v_pk_fma_f32 v[112:113], v[112:113], v[116:117], v[114:115]
	s_nop 0
	ds_read_b32 v245, v248 offset:12800
	s_waitcnt lgkmcnt(3)
	v_mov_b32_e32 v115, v246
	v_lshlrev_b32_e32 v114, 16, v115
	v_and_b32_e32 v115, 0xffff0000, v115
	v_pk_fma_f32 v[116:117], v[80:81], v[114:115], v[118:119]
	v_pk_fma_f32 v[118:119], v[82:83], v[114:115], v[120:121]
	v_pk_fma_f32 v[120:121], v[84:85], v[114:115], v[122:123]
	v_pk_fma_f32 v[122:123], v[86:87], v[114:115], v[124:125]
	v_pk_fma_f32 v[124:125], v[88:89], v[114:115], v[128:129]
	v_pk_fma_f32 v[128:129], v[90:91], v[114:115], v[166:167]
	v_pk_fma_f32 v[166:167], v[92:93], v[114:115], v[168:169]
	v_pk_fma_f32 v[168:169], v[94:95], v[114:115], v[170:171]
	v_pk_fma_f32 v[170:171], v[96:97], v[114:115], v[172:173]
	v_pk_fma_f32 v[172:173], v[98:99], v[114:115], v[174:175]
	v_pk_fma_f32 v[174:175], v[100:101], v[114:115], v[176:177]
	v_pk_fma_f32 v[176:177], v[102:103], v[114:115], v[178:179]
	v_pk_fma_f32 v[178:179], v[104:105], v[114:115], v[180:181]
	v_pk_fma_f32 v[180:181], v[106:107], v[114:115], v[182:183]
	v_pk_fma_f32 v[182:183], v[108:109], v[114:115], v[184:185]
	v_pk_fma_f32 v[110:111], v[110:111], v[114:115], v[112:113]
	s_nop 0
	ds_read_b32 v246, v248 offset:13312
	s_waitcnt lgkmcnt(3)
	v_mov_b32_e32 v113, v247
	v_lshlrev_b32_e32 v112, 16, v113
	v_and_b32_e32 v113, 0xffff0000, v113
	v_pk_fma_f32 v[114:115], v[78:79], v[112:113], v[116:117]
	v_pk_fma_f32 v[116:117], v[80:81], v[112:113], v[118:119]
	v_pk_fma_f32 v[118:119], v[82:83], v[112:113], v[120:121]
	v_pk_fma_f32 v[120:121], v[84:85], v[112:113], v[122:123]
	v_pk_fma_f32 v[122:123], v[86:87], v[112:113], v[124:125]
	v_pk_fma_f32 v[124:125], v[88:89], v[112:113], v[128:129]
	v_pk_fma_f32 v[128:129], v[90:91], v[112:113], v[166:167]
	v_pk_fma_f32 v[166:167], v[92:93], v[112:113], v[168:169]
	v_pk_fma_f32 v[168:169], v[94:95], v[112:113], v[170:171]
	v_pk_fma_f32 v[170:171], v[96:97], v[112:113], v[172:173]
	v_pk_fma_f32 v[172:173], v[98:99], v[112:113], v[174:175]
	v_pk_fma_f32 v[174:175], v[100:101], v[112:113], v[176:177]
	v_pk_fma_f32 v[176:177], v[102:103], v[112:113], v[178:179]
	v_pk_fma_f32 v[178:179], v[104:105], v[112:113], v[180:181]
	v_pk_fma_f32 v[180:181], v[106:107], v[112:113], v[182:183]
	v_pk_fma_f32 v[108:109], v[108:109], v[112:113], v[110:111]
	s_nop 0
	ds_read_b32 v247, v248 offset:13824
	s_waitcnt lgkmcnt(3)
	v_mov_b32_e32 v111, v244
	v_lshlrev_b32_e32 v110, 16, v111
	v_and_b32_e32 v111, 0xffff0000, v111
	v_pk_fma_f32 v[112:113], v[76:77], v[110:111], v[114:115]
	v_pk_fma_f32 v[114:115], v[78:79], v[110:111], v[116:117]
	v_pk_fma_f32 v[116:117], v[80:81], v[110:111], v[118:119]
	v_pk_fma_f32 v[118:119], v[82:83], v[110:111], v[120:121]
	v_pk_fma_f32 v[120:121], v[84:85], v[110:111], v[122:123]
	v_pk_fma_f32 v[122:123], v[86:87], v[110:111], v[124:125]
	v_pk_fma_f32 v[124:125], v[88:89], v[110:111], v[128:129]
	v_pk_fma_f32 v[128:129], v[90:91], v[110:111], v[166:167]
	v_pk_fma_f32 v[166:167], v[92:93], v[110:111], v[168:169]
	v_pk_fma_f32 v[168:169], v[94:95], v[110:111], v[170:171]
	v_pk_fma_f32 v[170:171], v[96:97], v[110:111], v[172:173]
	v_pk_fma_f32 v[172:173], v[98:99], v[110:111], v[174:175]
	v_pk_fma_f32 v[174:175], v[100:101], v[110:111], v[176:177]
	v_pk_fma_f32 v[176:177], v[102:103], v[110:111], v[178:179]
	v_pk_fma_f32 v[178:179], v[104:105], v[110:111], v[180:181]
	v_pk_fma_f32 v[106:107], v[106:107], v[110:111], v[108:109]
	s_nop 0
	ds_read_b32 v244, v248 offset:14336
	s_waitcnt lgkmcnt(3)
	v_mov_b32_e32 v109, v245
	v_lshlrev_b32_e32 v108, 16, v109
	v_and_b32_e32 v109, 0xffff0000, v109
	v_pk_fma_f32 v[110:111], v[74:75], v[108:109], v[112:113]
	v_pk_fma_f32 v[112:113], v[76:77], v[108:109], v[114:115]
	v_pk_fma_f32 v[114:115], v[78:79], v[108:109], v[116:117]
	v_pk_fma_f32 v[116:117], v[80:81], v[108:109], v[118:119]
	v_pk_fma_f32 v[118:119], v[82:83], v[108:109], v[120:121]
	v_pk_fma_f32 v[120:121], v[84:85], v[108:109], v[122:123]
	v_pk_fma_f32 v[122:123], v[86:87], v[108:109], v[124:125]
	v_pk_fma_f32 v[124:125], v[88:89], v[108:109], v[128:129]
	v_pk_fma_f32 v[128:129], v[90:91], v[108:109], v[166:167]
	v_pk_fma_f32 v[166:167], v[92:93], v[108:109], v[168:169]
	v_pk_fma_f32 v[168:169], v[94:95], v[108:109], v[170:171]
	v_pk_fma_f32 v[170:171], v[96:97], v[108:109], v[172:173]
	v_pk_fma_f32 v[172:173], v[98:99], v[108:109], v[174:175]
	v_pk_fma_f32 v[174:175], v[100:101], v[108:109], v[176:177]
	v_pk_fma_f32 v[176:177], v[102:103], v[108:109], v[178:179]
	v_pk_fma_f32 v[104:105], v[104:105], v[108:109], v[106:107]
	s_nop 0
	ds_read_b32 v245, v248 offset:14848
	s_waitcnt lgkmcnt(3)
	v_mov_b32_e32 v107, v246
	v_lshlrev_b32_e32 v106, 16, v107
	v_and_b32_e32 v107, 0xffff0000, v107
	v_pk_fma_f32 v[108:109], v[72:73], v[106:107], v[110:111]
	v_pk_fma_f32 v[110:111], v[74:75], v[106:107], v[112:113]
	v_pk_fma_f32 v[112:113], v[76:77], v[106:107], v[114:115]
	v_pk_fma_f32 v[114:115], v[78:79], v[106:107], v[116:117]
	v_pk_fma_f32 v[116:117], v[80:81], v[106:107], v[118:119]
	v_pk_fma_f32 v[118:119], v[82:83], v[106:107], v[120:121]
	v_pk_fma_f32 v[120:121], v[84:85], v[106:107], v[122:123]
	v_pk_fma_f32 v[122:123], v[86:87], v[106:107], v[124:125]
	v_pk_fma_f32 v[124:125], v[88:89], v[106:107], v[128:129]
	v_pk_fma_f32 v[128:129], v[90:91], v[106:107], v[166:167]
	v_pk_fma_f32 v[166:167], v[92:93], v[106:107], v[168:169]
	v_pk_fma_f32 v[168:169], v[94:95], v[106:107], v[170:171]
	v_pk_fma_f32 v[170:171], v[96:97], v[106:107], v[172:173]
	v_pk_fma_f32 v[172:173], v[98:99], v[106:107], v[174:175]
	v_pk_fma_f32 v[174:175], v[100:101], v[106:107], v[176:177]
	v_pk_fma_f32 v[102:103], v[102:103], v[106:107], v[104:105]
	s_nop 0
	ds_read_b32 v246, v248 offset:15360
	s_waitcnt lgkmcnt(3)
	v_mov_b32_e32 v105, v247
	v_lshlrev_b32_e32 v104, 16, v105
	v_and_b32_e32 v105, 0xffff0000, v105
	v_pk_fma_f32 v[106:107], v[70:71], v[104:105], v[108:109]
	v_pk_fma_f32 v[108:109], v[72:73], v[104:105], v[110:111]
	v_pk_fma_f32 v[110:111], v[74:75], v[104:105], v[112:113]
	v_pk_fma_f32 v[112:113], v[76:77], v[104:105], v[114:115]
	v_pk_fma_f32 v[114:115], v[78:79], v[104:105], v[116:117]
	v_pk_fma_f32 v[116:117], v[80:81], v[104:105], v[118:119]
	v_pk_fma_f32 v[118:119], v[82:83], v[104:105], v[120:121]
	v_pk_fma_f32 v[120:121], v[84:85], v[104:105], v[122:123]
	v_pk_fma_f32 v[122:123], v[86:87], v[104:105], v[124:125]
	v_pk_fma_f32 v[124:125], v[88:89], v[104:105], v[128:129]
	v_pk_fma_f32 v[128:129], v[90:91], v[104:105], v[166:167]
	v_pk_fma_f32 v[166:167], v[92:93], v[104:105], v[168:169]
	v_pk_fma_f32 v[168:169], v[94:95], v[104:105], v[170:171]
	v_pk_fma_f32 v[170:171], v[96:97], v[104:105], v[172:173]
	v_pk_fma_f32 v[172:173], v[98:99], v[104:105], v[174:175]
	v_pk_fma_f32 v[100:101], v[100:101], v[104:105], v[102:103]
	s_nop 0
	ds_read_b32 v247, v248 offset:15872
	s_waitcnt lgkmcnt(3)
	v_mov_b32_e32 v103, v244
	v_lshlrev_b32_e32 v102, 16, v103
	v_and_b32_e32 v103, 0xffff0000, v103
	v_pk_fma_f32 v[104:105], v[68:69], v[102:103], v[106:107]
	v_pk_fma_f32 v[106:107], v[70:71], v[102:103], v[108:109]
	v_pk_fma_f32 v[108:109], v[72:73], v[102:103], v[110:111]
	v_pk_fma_f32 v[110:111], v[74:75], v[102:103], v[112:113]
	v_pk_fma_f32 v[112:113], v[76:77], v[102:103], v[114:115]
	v_pk_fma_f32 v[114:115], v[78:79], v[102:103], v[116:117]
	v_pk_fma_f32 v[116:117], v[80:81], v[102:103], v[118:119]
	v_pk_fma_f32 v[118:119], v[82:83], v[102:103], v[120:121]
	v_pk_fma_f32 v[120:121], v[84:85], v[102:103], v[122:123]
	v_pk_fma_f32 v[122:123], v[86:87], v[102:103], v[124:125]
	v_pk_fma_f32 v[124:125], v[88:89], v[102:103], v[128:129]
	v_pk_fma_f32 v[128:129], v[90:91], v[102:103], v[166:167]
	v_pk_fma_f32 v[166:167], v[92:93], v[102:103], v[168:169]
	v_pk_fma_f32 v[168:169], v[94:95], v[102:103], v[170:171]
	v_pk_fma_f32 v[170:171], v[96:97], v[102:103], v[172:173]
	v_pk_fma_f32 v[98:99], v[98:99], v[102:103], v[100:101]
	s_nop 0
	ds_read_b32 v244, v248 offset:16384
	s_waitcnt lgkmcnt(3)
	v_mov_b32_e32 v101, v245
	v_lshlrev_b32_e32 v100, 16, v101
	v_and_b32_e32 v101, 0xffff0000, v101
	v_pk_fma_f32 v[102:103], v[66:67], v[100:101], v[104:105]
	v_pk_fma_f32 v[104:105], v[68:69], v[100:101], v[106:107]
	v_pk_fma_f32 v[106:107], v[70:71], v[100:101], v[108:109]
	v_pk_fma_f32 v[108:109], v[72:73], v[100:101], v[110:111]
	v_pk_fma_f32 v[110:111], v[74:75], v[100:101], v[112:113]
	v_pk_fma_f32 v[112:113], v[76:77], v[100:101], v[114:115]
	v_pk_fma_f32 v[114:115], v[78:79], v[100:101], v[116:117]
	v_pk_fma_f32 v[116:117], v[80:81], v[100:101], v[118:119]
	v_pk_fma_f32 v[118:119], v[82:83], v[100:101], v[120:121]
	v_pk_fma_f32 v[120:121], v[84:85], v[100:101], v[122:123]
	v_pk_fma_f32 v[122:123], v[86:87], v[100:101], v[124:125]
	v_pk_fma_f32 v[124:125], v[88:89], v[100:101], v[128:129]
	v_pk_fma_f32 v[128:129], v[90:91], v[100:101], v[166:167]
	v_pk_fma_f32 v[166:167], v[92:93], v[100:101], v[168:169]
	v_pk_fma_f32 v[168:169], v[94:95], v[100:101], v[170:171]
	v_pk_fma_f32 v[98:99], v[96:97], v[100:101], v[98:99]
	s_nop 0
	ds_read_b32 v245, v248 offset:16896
	s_waitcnt lgkmcnt(3)
	v_mov_b32_e32 v96, v246
	v_lshlrev_b32_e32 v100, 16, v96
	v_and_b32_e32 v101, 0xffff0000, v96
	v_pk_fma_f32 v[96:97], v[64:65], v[100:101], v[102:103]
	v_pk_fma_f32 v[102:103], v[66:67], v[100:101], v[104:105]
	v_pk_fma_f32 v[104:105], v[68:69], v[100:101], v[106:107]
	v_pk_fma_f32 v[106:107], v[70:71], v[100:101], v[108:109]
	v_pk_fma_f32 v[108:109], v[72:73], v[100:101], v[110:111]
	v_pk_fma_f32 v[110:111], v[74:75], v[100:101], v[112:113]
	v_pk_fma_f32 v[112:113], v[76:77], v[100:101], v[114:115]
	v_pk_fma_f32 v[114:115], v[78:79], v[100:101], v[116:117]
	v_pk_fma_f32 v[116:117], v[80:81], v[100:101], v[118:119]
	v_pk_fma_f32 v[118:119], v[82:83], v[100:101], v[120:121]
	v_pk_fma_f32 v[120:121], v[84:85], v[100:101], v[122:123]
	v_pk_fma_f32 v[122:123], v[86:87], v[100:101], v[124:125]
	v_pk_fma_f32 v[124:125], v[88:89], v[100:101], v[128:129]
	v_pk_fma_f32 v[128:129], v[90:91], v[100:101], v[166:167]
	v_pk_fma_f32 v[166:167], v[92:93], v[100:101], v[168:169]
	v_pk_fma_f32 v[98:99], v[94:95], v[100:101], v[98:99]
	s_nop 0
	ds_read_b32 v246, v248 offset:17408
	s_waitcnt lgkmcnt(3)
	v_mov_b32_e32 v94, v247
	v_lshlrev_b32_e32 v100, 16, v94
	v_and_b32_e32 v101, 0xffff0000, v94
	v_pk_fma_f32 v[94:95], v[64:65], v[100:101], v[102:103]
	v_pk_fma_f32 v[102:103], v[66:67], v[100:101], v[104:105]
	v_pk_fma_f32 v[104:105], v[68:69], v[100:101], v[106:107]
	v_pk_fma_f32 v[106:107], v[70:71], v[100:101], v[108:109]
	v_pk_fma_f32 v[108:109], v[72:73], v[100:101], v[110:111]
	v_pk_fma_f32 v[110:111], v[74:75], v[100:101], v[112:113]
	v_pk_fma_f32 v[112:113], v[76:77], v[100:101], v[114:115]
	v_pk_fma_f32 v[114:115], v[78:79], v[100:101], v[116:117]
	v_pk_fma_f32 v[116:117], v[80:81], v[100:101], v[118:119]
	v_pk_fma_f32 v[118:119], v[82:83], v[100:101], v[120:121]
	v_pk_fma_f32 v[120:121], v[84:85], v[100:101], v[122:123]
	v_pk_fma_f32 v[122:123], v[86:87], v[100:101], v[124:125]
	v_pk_fma_f32 v[124:125], v[88:89], v[100:101], v[128:129]
	v_pk_fma_f32 v[128:129], v[90:91], v[100:101], v[166:167]
	v_pk_fma_f32 v[98:99], v[92:93], v[100:101], v[98:99]
	s_nop 0
	ds_read_b32 v247, v248 offset:17920
	s_waitcnt lgkmcnt(3)
	v_mov_b32_e32 v92, v244
	v_lshlrev_b32_e32 v100, 16, v92
	v_and_b32_e32 v101, 0xffff0000, v92
	v_pk_fma_f32 v[92:93], v[64:65], v[100:101], v[102:103]
	v_pk_fma_f32 v[102:103], v[66:67], v[100:101], v[104:105]
	v_pk_fma_f32 v[104:105], v[68:69], v[100:101], v[106:107]
	v_pk_fma_f32 v[106:107], v[70:71], v[100:101], v[108:109]
	v_pk_fma_f32 v[108:109], v[72:73], v[100:101], v[110:111]
	v_pk_fma_f32 v[110:111], v[74:75], v[100:101], v[112:113]
	v_pk_fma_f32 v[112:113], v[76:77], v[100:101], v[114:115]
	v_pk_fma_f32 v[114:115], v[78:79], v[100:101], v[116:117]
	v_pk_fma_f32 v[116:117], v[80:81], v[100:101], v[118:119]
	v_pk_fma_f32 v[118:119], v[82:83], v[100:101], v[120:121]
	v_pk_fma_f32 v[120:121], v[84:85], v[100:101], v[122:123]
	v_pk_fma_f32 v[122:123], v[86:87], v[100:101], v[124:125]
	v_pk_fma_f32 v[124:125], v[88:89], v[100:101], v[128:129]
	v_pk_fma_f32 v[98:99], v[90:91], v[100:101], v[98:99]
	s_nop 0
	ds_read_b32 v244, v248 offset:18432
	s_waitcnt lgkmcnt(3)
	v_mov_b32_e32 v90, v245
	v_lshlrev_b32_e32 v100, 16, v90
	v_and_b32_e32 v101, 0xffff0000, v90
	v_pk_fma_f32 v[90:91], v[64:65], v[100:101], v[102:103]
	v_pk_fma_f32 v[102:103], v[66:67], v[100:101], v[104:105]
	v_pk_fma_f32 v[104:105], v[68:69], v[100:101], v[106:107]
	v_pk_fma_f32 v[106:107], v[70:71], v[100:101], v[108:109]
	v_pk_fma_f32 v[108:109], v[72:73], v[100:101], v[110:111]
	v_pk_fma_f32 v[110:111], v[74:75], v[100:101], v[112:113]
	v_pk_fma_f32 v[112:113], v[76:77], v[100:101], v[114:115]
	v_pk_fma_f32 v[114:115], v[78:79], v[100:101], v[116:117]
	v_pk_fma_f32 v[116:117], v[80:81], v[100:101], v[118:119]
	v_pk_fma_f32 v[118:119], v[82:83], v[100:101], v[120:121]
	v_pk_fma_f32 v[120:121], v[84:85], v[100:101], v[122:123]
	v_pk_fma_f32 v[122:123], v[86:87], v[100:101], v[124:125]
	v_pk_fma_f32 v[98:99], v[88:89], v[100:101], v[98:99]
	s_nop 0
	ds_read_b32 v245, v248 offset:18944
	s_waitcnt lgkmcnt(3)
	v_mov_b32_e32 v88, v246
	v_lshlrev_b32_e32 v100, 16, v88
	v_and_b32_e32 v101, 0xffff0000, v88
	v_pk_fma_f32 v[88:89], v[64:65], v[100:101], v[102:103]
	v_pk_fma_f32 v[102:103], v[66:67], v[100:101], v[104:105]
	v_pk_fma_f32 v[104:105], v[68:69], v[100:101], v[106:107]
	v_pk_fma_f32 v[106:107], v[70:71], v[100:101], v[108:109]
	v_pk_fma_f32 v[108:109], v[72:73], v[100:101], v[110:111]
	v_pk_fma_f32 v[110:111], v[74:75], v[100:101], v[112:113]
	v_pk_fma_f32 v[112:113], v[76:77], v[100:101], v[114:115]
	v_pk_fma_f32 v[114:115], v[78:79], v[100:101], v[116:117]
	v_pk_fma_f32 v[116:117], v[80:81], v[100:101], v[118:119]
	v_pk_fma_f32 v[118:119], v[82:83], v[100:101], v[120:121]
	v_pk_fma_f32 v[120:121], v[84:85], v[100:101], v[122:123]
	v_pk_fma_f32 v[98:99], v[86:87], v[100:101], v[98:99]
	s_nop 0
	ds_read_b32 v246, v248 offset:19456
	s_waitcnt lgkmcnt(3)
	v_mov_b32_e32 v86, v247
	v_lshlrev_b32_e32 v100, 16, v86
	v_and_b32_e32 v101, 0xffff0000, v86
	v_pk_fma_f32 v[86:87], v[64:65], v[100:101], v[102:103]
	v_pk_fma_f32 v[102:103], v[66:67], v[100:101], v[104:105]
	v_pk_fma_f32 v[104:105], v[68:69], v[100:101], v[106:107]
	v_pk_fma_f32 v[106:107], v[70:71], v[100:101], v[108:109]
	v_pk_fma_f32 v[108:109], v[72:73], v[100:101], v[110:111]
	v_pk_fma_f32 v[110:111], v[74:75], v[100:101], v[112:113]
	v_pk_fma_f32 v[112:113], v[76:77], v[100:101], v[114:115]
	v_pk_fma_f32 v[114:115], v[78:79], v[100:101], v[116:117]
	v_pk_fma_f32 v[116:117], v[80:81], v[100:101], v[118:119]
	v_pk_fma_f32 v[118:119], v[82:83], v[100:101], v[120:121]
	v_pk_fma_f32 v[98:99], v[84:85], v[100:101], v[98:99]
	s_nop 0
	ds_read_b32 v247, v248 offset:19968
	s_waitcnt lgkmcnt(3)
	v_mov_b32_e32 v84, v244
	v_lshlrev_b32_e32 v100, 16, v84
	v_and_b32_e32 v101, 0xffff0000, v84
	v_pk_fma_f32 v[84:85], v[64:65], v[100:101], v[102:103]
	v_pk_fma_f32 v[102:103], v[66:67], v[100:101], v[104:105]
	v_pk_fma_f32 v[104:105], v[68:69], v[100:101], v[106:107]
	v_pk_fma_f32 v[106:107], v[70:71], v[100:101], v[108:109]
	v_pk_fma_f32 v[108:109], v[72:73], v[100:101], v[110:111]
	v_pk_fma_f32 v[110:111], v[74:75], v[100:101], v[112:113]
	v_pk_fma_f32 v[112:113], v[76:77], v[100:101], v[114:115]
	v_pk_fma_f32 v[114:115], v[78:79], v[100:101], v[116:117]
	v_pk_fma_f32 v[116:117], v[80:81], v[100:101], v[118:119]
	v_pk_fma_f32 v[98:99], v[82:83], v[100:101], v[98:99]
	s_nop 0
	ds_read_b32 v244, v248 offset:20480
	s_waitcnt lgkmcnt(3)
	v_mov_b32_e32 v82, v245
	v_lshlrev_b32_e32 v100, 16, v82
	v_and_b32_e32 v101, 0xffff0000, v82
	v_pk_fma_f32 v[82:83], v[64:65], v[100:101], v[102:103]
	v_pk_fma_f32 v[102:103], v[66:67], v[100:101], v[104:105]
	v_pk_fma_f32 v[104:105], v[68:69], v[100:101], v[106:107]
	v_pk_fma_f32 v[106:107], v[70:71], v[100:101], v[108:109]
	v_pk_fma_f32 v[108:109], v[72:73], v[100:101], v[110:111]
	v_pk_fma_f32 v[110:111], v[74:75], v[100:101], v[112:113]
	v_pk_fma_f32 v[112:113], v[76:77], v[100:101], v[114:115]
	v_pk_fma_f32 v[114:115], v[78:79], v[100:101], v[116:117]
	v_pk_fma_f32 v[98:99], v[80:81], v[100:101], v[98:99]
	s_nop 0
	ds_read_b32 v245, v248 offset:20992
	s_waitcnt lgkmcnt(3)
	v_mov_b32_e32 v80, v246
	v_lshlrev_b32_e32 v100, 16, v80
	v_and_b32_e32 v101, 0xffff0000, v80
	v_pk_fma_f32 v[80:81], v[64:65], v[100:101], v[102:103]
	v_pk_fma_f32 v[102:103], v[66:67], v[100:101], v[104:105]
	v_pk_fma_f32 v[104:105], v[68:69], v[100:101], v[106:107]
	v_pk_fma_f32 v[106:107], v[70:71], v[100:101], v[108:109]
	v_pk_fma_f32 v[108:109], v[72:73], v[100:101], v[110:111]
	v_pk_fma_f32 v[110:111], v[74:75], v[100:101], v[112:113]
	v_pk_fma_f32 v[112:113], v[76:77], v[100:101], v[114:115]
	v_pk_fma_f32 v[98:99], v[78:79], v[100:101], v[98:99]
	s_nop 0
	ds_read_b32 v246, v248 offset:21504
	s_waitcnt lgkmcnt(3)
	v_mov_b32_e32 v78, v247
	v_lshlrev_b32_e32 v100, 16, v78
	v_and_b32_e32 v101, 0xffff0000, v78
	v_pk_fma_f32 v[78:79], v[64:65], v[100:101], v[102:103]
	v_pk_fma_f32 v[102:103], v[66:67], v[100:101], v[104:105]
	v_pk_fma_f32 v[104:105], v[68:69], v[100:101], v[106:107]
	v_pk_fma_f32 v[106:107], v[70:71], v[100:101], v[108:109]
	v_pk_fma_f32 v[108:109], v[72:73], v[100:101], v[110:111]
	v_pk_fma_f32 v[110:111], v[74:75], v[100:101], v[112:113]
	v_pk_fma_f32 v[76:77], v[76:77], v[100:101], v[98:99]
	s_nop 0
	ds_read_b32 v247, v248 offset:22016
	s_waitcnt lgkmcnt(3)
	v_mov_b32_e32 v99, v244
	v_lshlrev_b32_e32 v98, 16, v99
	v_and_b32_e32 v99, 0xffff0000, v99
	v_pk_fma_f32 v[100:101], v[64:65], v[98:99], v[102:103]
	v_pk_fma_f32 v[102:103], v[66:67], v[98:99], v[104:105]
	v_pk_fma_f32 v[104:105], v[68:69], v[98:99], v[106:107]
	v_pk_fma_f32 v[106:107], v[70:71], v[98:99], v[108:109]
	v_pk_fma_f32 v[108:109], v[72:73], v[98:99], v[110:111]
	v_pk_fma_f32 v[74:75], v[74:75], v[98:99], v[76:77]
	v_and_b32_e32 v110, 63, v156
	ds_read_b32 v244, v248 offset:22528
	s_waitcnt lgkmcnt(3)
	v_mov_b32_e32 v77, v245
	v_lshlrev_b32_e32 v76, 16, v77
	v_and_b32_e32 v77, 0xffff0000, v77
	v_pk_fma_f32 v[98:99], v[64:65], v[76:77], v[102:103]
	v_pk_fma_f32 v[102:103], v[66:67], v[76:77], v[104:105]
	v_pk_fma_f32 v[104:105], v[68:69], v[76:77], v[106:107]
	v_pk_fma_f32 v[106:107], v[70:71], v[76:77], v[108:109]
	v_pk_fma_f32 v[72:73], v[72:73], v[76:77], v[74:75]
	s_nop 0
	ds_read_b32 v245, v248 offset:23040
	s_waitcnt lgkmcnt(3)
	v_mov_b32_e32 v75, v246
	v_lshlrev_b32_e32 v74, 16, v75
	v_and_b32_e32 v75, 0xffff0000, v75
	v_pk_fma_f32 v[76:77], v[64:65], v[74:75], v[102:103]
	v_pk_fma_f32 v[102:103], v[66:67], v[74:75], v[104:105]
	v_pk_fma_f32 v[104:105], v[68:69], v[74:75], v[106:107]
	v_pk_fma_f32 v[70:71], v[70:71], v[74:75], v[72:73]
	s_nop 0
	s_waitcnt lgkmcnt(2)
	v_mov_b32_e32 v73, v247
	v_lshlrev_b32_e32 v72, 16, v73
	v_and_b32_e32 v73, 0xffff0000, v73
	v_pk_fma_f32 v[74:75], v[64:65], v[72:73], v[102:103]
	v_pk_fma_f32 v[102:103], v[66:67], v[72:73], v[104:105]
	v_pk_fma_f32 v[68:69], v[68:69], v[72:73], v[70:71]
	s_nop 0
	s_waitcnt lgkmcnt(1)
	v_mov_b32_e32 v71, v244
	v_lshlrev_b32_e32 v70, 16, v71
	v_and_b32_e32 v71, 0xffff0000, v71
	v_pk_fma_f32 v[72:73], v[64:65], v[70:71], v[102:103]
	v_pk_fma_f32 v[66:67], v[66:67], v[70:71], v[68:69]
	s_nop 0
	s_waitcnt lgkmcnt(0)
	v_mov_b32_e32 v69, v245
	v_lshlrev_b32_e32 v68, 16, v69
	v_and_b32_e32 v69, 0xffff0000, v69
	v_pk_fma_f32 v[64:65], v[64:65], v[68:69], v[66:67]
	v_lshl_add_u32 v66, v157, 3, 0
	v_lshl_add_u32 v67, v159, 10, v66
	ds_write_b64 v67, v[96:97] offset:48128
	v_lshl_add_u32 v67, v160, 10, v66
	ds_write_b64 v67, v[94:95] offset:48128
	v_lshl_add_u32 v67, v126, 10, v66
	ds_write_b64 v67, v[92:93] offset:48128
	v_lshl_add_u32 v67, v127, 10, v66
	ds_write_b64 v67, v[90:91] offset:48128
	v_lshl_add_u32 v67, v162, 10, v66
	ds_write_b64 v67, v[88:89] offset:48128
	v_lshl_add_u32 v67, v163, 10, v66
	ds_write_b64 v67, v[86:87] offset:48128
	v_lshl_add_u32 v67, v164, 10, v66
	ds_write_b64 v67, v[84:85] offset:48128
	v_lshl_add_u32 v67, v165, 10, v66
	ds_write_b64 v67, v[82:83] offset:48128
	v_lshl_add_u32 v67, v144, 10, v66
	ds_write_b64 v67, v[80:81] offset:48128
	v_lshl_add_u32 v67, v142, 10, v66
	ds_write_b64 v67, v[78:79] offset:48128
	v_lshl_add_u32 v67, v140, 10, v66
	ds_write_b64 v67, v[100:101] offset:48128
	v_lshl_add_u32 v67, v138, 10, v66
	ds_write_b64 v67, v[98:99] offset:48128
	v_lshl_add_u32 v67, v136, 10, v66
	ds_write_b64 v67, v[76:77] offset:48128
	v_lshl_add_u32 v67, v134, 10, v66
	ds_write_b64 v67, v[74:75] offset:48128
	v_lshl_add_u32 v67, v132, 10, v66
	v_lshl_add_u32 v66, v130, 10, v66
	v_lshlrev_b32_e32 v68, 4, v110
	ds_write_b64 v67, v[72:73] offset:48128
	ds_write_b64 v66, v[64:65] offset:48128
	s_waitcnt lgkmcnt(0)
	s_barrier
	global_load_dwordx4 v[64:67], v68, s[42:43]
	v_readlane_b32 s42, v255, 7
	v_readlane_b32 s43, v255, 8
	v_add_u32_e32 v106, s23, v68
	ds_read_b128 v[100:103], v106 offset:48128
	ds_read_b128 v[96:99], v106 offset:49152
	ds_read_b128 v[92:95], v106 offset:50176
	ds_read_b128 v[88:91], v106 offset:51200
	global_load_dwordx4 v[68:71], v68, s[42:43]
	s_waitcnt lgkmcnt(3)
	v_mov_b32_e32 v72, v101
	v_mov_b32_e32 v73, v102
	v_mov_b32_e32 v74, v100
	v_mov_b32_e32 v75, v103
	v_pk_add_f32 v[72:73], v[72:73], v[74:75]
	v_pk_mul_f32 v[74:75], v[100:101], v[100:101]
	v_add_f32_e32 v111, v72, v73
	v_pk_mul_f32 v[72:73], v[102:103], v[102:103]
	ds_read_b128 v[84:87], v106 offset:52224
	ds_read_b128 v[80:83], v106 offset:53248
	v_pk_mov_b32 v[76:77], v[74:75], v[72:73] op_sel:[1,0]
	v_mov_b32_e32 v75, v73
	v_pk_add_f32 v[72:73], v[76:77], v[74:75]
	s_waitcnt lgkmcnt(4)
	v_mov_b32_e32 v74, v96
	v_add_f32_e32 v112, v72, v73
	v_mov_b32_e32 v72, v97
	v_mov_b32_e32 v73, v98
	v_mov_b32_e32 v75, v99
	v_pk_add_f32 v[72:73], v[72:73], v[74:75]
	v_pk_mul_f32 v[74:75], v[96:97], v[96:97]
	v_add_f32_e32 v113, v72, v73
	v_pk_mul_f32 v[72:73], v[98:99], v[98:99]
	s_nop 0
	v_pk_mov_b32 v[76:77], v[74:75], v[72:73] op_sel:[1,0]
	v_mov_b32_e32 v75, v73
	v_pk_add_f32 v[72:73], v[76:77], v[74:75]
	s_waitcnt lgkmcnt(3)
	v_mov_b32_e32 v74, v92
	v_add_f32_e32 v114, v72, v73
	v_mov_b32_e32 v72, v93
	v_mov_b32_e32 v73, v94
	v_mov_b32_e32 v75, v95
	v_pk_add_f32 v[72:73], v[72:73], v[74:75]
	v_pk_mul_f32 v[74:75], v[92:93], v[92:93]
	v_add_f32_e32 v115, v72, v73
	v_pk_mul_f32 v[72:73], v[94:95], v[94:95]
	s_nop 0
	v_pk_mov_b32 v[76:77], v[74:75], v[72:73] op_sel:[1,0]
	v_mov_b32_e32 v75, v73
	v_pk_add_f32 v[72:73], v[76:77], v[74:75]
	s_waitcnt lgkmcnt(2)
	v_mov_b32_e32 v74, v88
	v_add_f32_e32 v116, v72, v73
	v_mov_b32_e32 v72, v89
	v_mov_b32_e32 v73, v90
	v_mov_b32_e32 v75, v91
	v_pk_add_f32 v[72:73], v[72:73], v[74:75]
	v_pk_mul_f32 v[74:75], v[88:89], v[88:89]
	v_add_f32_e32 v117, v72, v73
	v_pk_mul_f32 v[72:73], v[90:91], v[90:91]
	s_nop 0
	v_pk_mov_b32 v[76:77], v[74:75], v[72:73] op_sel:[1,0]
	v_mov_b32_e32 v75, v73
	v_pk_add_f32 v[72:73], v[76:77], v[74:75]
	s_waitcnt lgkmcnt(1)
	v_mov_b32_e32 v74, v84
	v_add_f32_e32 v118, v72, v73
	v_mov_b32_e32 v72, v85
	v_mov_b32_e32 v73, v86
	v_mov_b32_e32 v75, v87
	v_pk_add_f32 v[72:73], v[72:73], v[74:75]
	v_pk_mul_f32 v[74:75], v[84:85], v[84:85]
	v_add_f32_e32 v119, v72, v73
	v_pk_mul_f32 v[72:73], v[86:87], v[86:87]
	s_nop 0
	v_pk_mov_b32 v[76:77], v[74:75], v[72:73] op_sel:[1,0]
	v_mov_b32_e32 v75, v73
	v_pk_add_f32 v[72:73], v[76:77], v[74:75]
	s_waitcnt lgkmcnt(0)
	v_mov_b32_e32 v74, v80
	v_add_f32_e32 v120, v72, v73
	v_mov_b32_e32 v72, v81
	v_mov_b32_e32 v73, v82
	v_mov_b32_e32 v75, v83
	ds_read_b128 v[76:79], v106 offset:54272
	v_pk_add_f32 v[72:73], v[72:73], v[74:75]
	v_pk_mul_f32 v[74:75], v[80:81], v[80:81]
	v_add_f32_e32 v121, v72, v73
	v_pk_mul_f32 v[72:73], v[82:83], v[82:83]
	s_nop 0
	v_pk_mov_b32 v[104:105], v[74:75], v[72:73] op_sel:[1,0]
	v_mov_b32_e32 v75, v73
	v_pk_add_f32 v[72:73], v[104:105], v[74:75]
	s_nop 0
	v_add_f32_e32 v122, v72, v73
	ds_read_b128 v[72:75], v106 offset:55296
	s_waitcnt lgkmcnt(1)
	v_mov_b32_e32 v104, v77
	v_mov_b32_e32 v105, v78
	v_mov_b32_e32 v106, v76
	v_mov_b32_e32 v107, v79
	v_pk_add_f32 v[104:105], v[104:105], v[106:107]
	v_pk_mul_f32 v[106:107], v[76:77], v[76:77]
	v_add_f32_e32 v123, v104, v105
	v_pk_mul_f32 v[104:105], v[78:79], v[78:79]
	s_nop 0
	v_pk_mov_b32 v[108:109], v[106:107], v[104:105] op_sel:[1,0]
	v_mov_b32_e32 v107, v105
	v_pk_add_f32 v[104:105], v[108:109], v[106:107]
	s_waitcnt lgkmcnt(0)
	v_mov_b32_e32 v106, v72
	v_add_f32_e32 v124, v104, v105
	v_mov_b32_e32 v104, v73
	v_mov_b32_e32 v105, v74
	v_mov_b32_e32 v107, v75
	v_pk_add_f32 v[104:105], v[104:105], v[106:107]
	v_pk_mul_f32 v[106:107], v[72:73], v[72:73]
	v_add_f32_e32 v125, v104, v105
	v_pk_mul_f32 v[104:105], v[74:75], v[74:75]
	s_nop 0
	v_pk_mov_b32 v[108:109], v[106:107], v[104:105] op_sel:[1,0]
	v_mov_b32_e32 v107, v105
	v_pk_add_f32 v[104:105], v[108:109], v[106:107]
	v_add_f32_dpp v106, v112, v112 quad_perm:[1,0,3,2] row_mask:0xf bank_mask:0xf bound_ctrl:1
	v_add_f32_e32 v104, v104, v105
	v_add_f32_dpp v105, v111, v111 quad_perm:[1,0,3,2] row_mask:0xf bank_mask:0xf bound_ctrl:1
	v_add_f32_dpp v111, v116, v116 quad_perm:[1,0,3,2] row_mask:0xf bank_mask:0xf bound_ctrl:1
	v_add_f32_dpp v104, v104, v104 quad_perm:[1,0,3,2] row_mask:0xf bank_mask:0xf bound_ctrl:1
	v_add_f32_dpp v105, v105, v105 quad_perm:[2,3,0,1] row_mask:0xf bank_mask:0xf bound_ctrl:1
	v_add_f32_dpp v116, v121, v121 quad_perm:[1,0,3,2] row_mask:0xf bank_mask:0xf bound_ctrl:1
	v_add_f32_dpp v104, v104, v104 quad_perm:[2,3,0,1] row_mask:0xf bank_mask:0xf bound_ctrl:1
	v_add_f32_dpp v105, v105, v105 row_half_mirror row_mask:0xf bank_mask:0xf bound_ctrl:1
	v_add_f32_dpp v106, v106, v106 quad_perm:[2,3,0,1] row_mask:0xf bank_mask:0xf bound_ctrl:1
	v_add_f32_dpp v121, v104, v104 row_half_mirror row_mask:0xf bank_mask:0xf bound_ctrl:1
	v_add_f32_dpp v104, v105, v105 row_mirror row_mask:0xf bank_mask:0xf bound_ctrl:1
	v_add_f32_dpp v106, v106, v106 row_half_mirror row_mask:0xf bank_mask:0xf bound_ctrl:1
	v_readlane_b32 s23, v104, 16
	v_readlane_b32 s44, v104, 48
	v_add_f32_dpp v107, v113, v113 quad_perm:[1,0,3,2] row_mask:0xf bank_mask:0xf bound_ctrl:1
	v_add_f32_dpp v112, v117, v117 quad_perm:[1,0,3,2] row_mask:0xf bank_mask:0xf bound_ctrl:1
	v_add_f32_dpp v117, v122, v122 quad_perm:[1,0,3,2] row_mask:0xf bank_mask:0xf bound_ctrl:1
	v_add_f32_dpp v122, v106, v106 row_mirror row_mask:0xf bank_mask:0xf bound_ctrl:1
	v_readlane_b32 s42, v104, 0
	v_readlane_b32 s43, v104, 32
	v_mov_b32_e32 v104, s23
	v_mov_b32_e32 v105, s44
	v_add_f32_dpp v108, v114, v114 quad_perm:[1,0,3,2] row_mask:0xf bank_mask:0xf bound_ctrl:1
	v_add_f32_dpp v109, v115, v115 quad_perm:[1,0,3,2] row_mask:0xf bank_mask:0xf bound_ctrl:1
	v_add_f32_dpp v107, v107, v107 quad_perm:[2,3,0,1] row_mask:0xf bank_mask:0xf bound_ctrl:1
	v_pk_add_f32 v[104:105], s[42:43], v[104:105]
	v_readlane_b32 s42, v122, 16
	v_add_f32_dpp v108, v108, v108 quad_perm:[2,3,0,1] row_mask:0xf bank_mask:0xf bound_ctrl:1
	v_add_f32_dpp v109, v109, v109 quad_perm:[2,3,0,1] row_mask:0xf bank_mask:0xf bound_ctrl:1
	v_add_f32_dpp v107, v107, v107 row_half_mirror row_mask:0xf bank_mask:0xf bound_ctrl:1
	v_readlane_b32 s23, v122, 0
	v_mov_b32_e32 v106, s42
	v_readlane_b32 s42, v122, 48
	v_add_f32_dpp v113, v118, v118 quad_perm:[1,0,3,2] row_mask:0xf bank_mask:0xf bound_ctrl:1
	v_add_f32_dpp v118, v123, v123 quad_perm:[1,0,3,2] row_mask:0xf bank_mask:0xf bound_ctrl:1
	v_add_f32_dpp v108, v108, v108 row_half_mirror row_mask:0xf bank_mask:0xf bound_ctrl:1
	v_add_f32_dpp v109, v109, v109 row_half_mirror row_mask:0xf bank_mask:0xf bound_ctrl:1
	v_add_f32_dpp v123, v107, v107 row_mirror row_mask:0xf bank_mask:0xf bound_ctrl:1
	v_add_f32_e32 v106, s23, v106
	v_readlane_b32 s23, v122, 32
	v_mov_b32_e32 v107, s42
	v_add_f32_dpp v114, v119, v119 quad_perm:[1,0,3,2] row_mask:0xf bank_mask:0xf bound_ctrl:1
	v_add_f32_dpp v115, v120, v120 quad_perm:[1,0,3,2] row_mask:0xf bank_mask:0xf bound_ctrl:1
	v_add_f32_dpp v119, v124, v124 quad_perm:[1,0,3,2] row_mask:0xf bank_mask:0xf bound_ctrl:1
	v_add_f32_dpp v120, v125, v125 quad_perm:[1,0,3,2] row_mask:0xf bank_mask:0xf bound_ctrl:1
	v_add_f32_dpp v124, v108, v108 row_mirror row_mask:0xf bank_mask:0xf bound_ctrl:1
	v_add_f32_dpp v125, v109, v109 row_mirror row_mask:0xf bank_mask:0xf bound_ctrl:1
	v_add_f32_e32 v108, s23, v107
	v_mov_b32_e32 v107, v104
	v_mov_b32_e32 v109, v105
	v_pk_add_f32 v[104:105], v[106:107], v[108:109]
	v_readlane_b32 s23, v123, 16
	v_pk_mul_f32 v[104:105], v[104:105], s[46:47] op_sel_hi:[1,0]
	v_readlane_b32 s44, v123, 48
	v_fma_f32 v106, -v105, v105, v104
	v_max_f32_e32 v106, 0, v106
	v_add_f32_e32 v106, 0x3727c5ac, v106
	v_rsq_f32_e32 v106, v106
	v_pk_add_f32 v[100:101], v[100:101], v[104:105] op_sel:[0,1] neg_lo:[0,1] neg_hi:[0,1]
	v_pk_add_f32 v[102:103], v[102:103], v[104:105] op_sel:[0,1] neg_lo:[0,1] neg_hi:[0,1]
	v_readlane_b32 s42, v123, 0
	v_pk_mul_f32 v[100:101], v[100:101], v[106:107] op_sel_hi:[1,0]
	v_readlane_b32 s43, v123, 32
	s_waitcnt vmcnt(0)
	v_pk_fma_f32 v[100:101], v[64:65], v[100:101], v[68:69]
	v_add_f32_dpp v111, v111, v111 quad_perm:[2,3,0,1] row_mask:0xf bank_mask:0xf bound_ctrl:1
	v_mul_f32_e32 v107, 0xbfb8aa3b, v100
	v_exp_f32_e32 v107, v107
	v_mul_f32_e32 v108, 0xbfb8aa3b, v101
	v_exp_f32_e32 v109, v108
	v_add_f32_dpp v111, v111, v111 row_half_mirror row_mask:0xf bank_mask:0xf bound_ctrl:1
	v_add_f32_e32 v107, 1.0, v107
	v_rcp_f32_e32 v108, v107
	v_add_f32_e32 v107, 1.0, v109
	v_pk_mul_f32 v[102:103], v[102:103], v[106:107] op_sel_hi:[1,0]
	v_rcp_f32_e32 v109, v107
	v_pk_fma_f32 v[102:103], v[66:67], v[102:103], v[70:71]
	v_add_f32_dpp v111, v111, v111 row_mirror row_mask:0xf bank_mask:0xf bound_ctrl:1
	v_mul_f32_e32 v104, 0xbfb8aa3b, v102
	v_mul_f32_e32 v105, 0xbfb8aa3b, v103
	v_exp_f32_e32 v104, v104
	v_exp_f32_e32 v105, v105
	v_pk_mul_f32 v[100:101], v[100:101], v[108:109]
	v_add_f32_dpp v112, v112, v112 quad_perm:[2,3,0,1] row_mask:0xf bank_mask:0xf bound_ctrl:1
	v_add_f32_e32 v104, 1.0, v104
	v_add_f32_e32 v105, 1.0, v105
	v_rcp_f32_e32 v104, v104
	v_rcp_f32_e32 v105, v105
	v_cvt_pk_bf16_f32 v100, v100, v101
	v_add_f32_dpp v113, v113, v113 quad_perm:[2,3,0,1] row_mask:0xf bank_mask:0xf bound_ctrl:1
	v_add_f32_dpp v112, v112, v112 row_half_mirror row_mask:0xf bank_mask:0xf bound_ctrl:1
	v_pk_mul_f32 v[102:103], v[102:103], v[104:105]
	v_add_f32_dpp v113, v113, v113 row_half_mirror row_mask:0xf bank_mask:0xf bound_ctrl:1
	v_cvt_pk_bf16_f32 v101, v102, v103
	v_mov_b32_e32 v102, s23
	v_mov_b32_e32 v103, s44
	v_pk_add_f32 v[102:103], s[42:43], v[102:103]
	v_readlane_b32 s42, v124, 16
	v_readlane_b32 s23, v124, 0
	v_mov_b32_e32 v107, v103
	v_mov_b32_e32 v104, s42
	v_readlane_b32 s42, v124, 48
	v_add_f32_e32 v104, s23, v104
	v_readlane_b32 s23, v124, 32
	v_mov_b32_e32 v105, s42
	v_readlane_b32 s42, v125, 0
	v_add_f32_e32 v106, s23, v105
	v_mov_b32_e32 v105, v102
	v_pk_add_f32 v[102:103], v[104:105], v[106:107]
	s_mul_i32 s23, s27, 0x1080
	v_pk_mul_f32 v[102:103], v[102:103], s[46:47] op_sel_hi:[1,0]
	s_add_i32 s23, s23, 0
	v_fma_f32 v104, -v103, v103, v102
	v_max_f32_e32 v104, 0, v104
	v_add_f32_e32 v104, 0x3727c5ac, v104
	v_rsq_f32_e32 v104, v104
	v_pk_add_f32 v[96:97], v[96:97], v[102:103] op_sel:[0,1] neg_lo:[0,1] neg_hi:[0,1]
	v_pk_add_f32 v[98:99], v[98:99], v[102:103] op_sel:[0,1] neg_lo:[0,1] neg_hi:[0,1]
	v_readlane_b32 s27, v125, 48
	v_pk_mul_f32 v[96:97], v[96:97], v[104:105] op_sel_hi:[1,0]
	v_lshl_add_u32 v122, v110, 3, s23
	v_pk_fma_f32 v[96:97], v[64:65], v[96:97], v[68:69]
	v_readlane_b32 s23, v125, 16
	v_mul_f32_e32 v105, 0xbfb8aa3b, v96
	v_exp_f32_e32 v105, v105
	v_mul_f32_e32 v106, 0xbfb8aa3b, v97
	v_exp_f32_e32 v107, v106
	v_readlane_b32 s43, v125, 32
	v_add_f32_e32 v105, 1.0, v105
	v_rcp_f32_e32 v106, v105
	v_add_f32_e32 v105, 1.0, v107
	v_pk_mul_f32 v[98:99], v[98:99], v[104:105] op_sel_hi:[1,0]
	v_rcp_f32_e32 v107, v105
	v_mov_b32_e32 v105, s27
	v_readlane_b32 s27, v111, 16
	v_mov_b32_e32 v104, s23
	v_readlane_b32 s23, v111, 0
	v_mov_b32_e32 v108, s27
	v_readlane_b32 s27, v111, 48
	v_pk_add_f32 v[104:105], s[42:43], v[104:105]
	v_add_f32_e32 v108, s23, v108
	v_readlane_b32 s23, v111, 32
	v_mov_b32_e32 v109, s27
	v_mov_b32_e32 v111, v105
	v_add_f32_e32 v110, s23, v109
	v_mov_b32_e32 v109, v104
	v_pk_fma_f32 v[98:99], v[66:67], v[98:99], v[70:71]
	v_pk_add_f32 v[104:105], v[108:109], v[110:111]
	v_mul_f32_e32 v102, 0xbfb8aa3b, v98
	v_mul_f32_e32 v103, 0xbfb8aa3b, v99
	v_pk_mul_f32 v[104:105], v[104:105], s[46:47] op_sel_hi:[1,0]
	v_exp_f32_e32 v102, v102
	v_exp_f32_e32 v103, v103
	v_fma_f32 v108, -v105, v105, v104
	v_max_f32_e32 v108, 0, v108
	v_add_f32_e32 v108, 0x3727c5ac, v108
	v_rsq_f32_e32 v108, v108
	v_add_f32_e32 v102, 1.0, v102
	v_add_f32_e32 v103, 1.0, v103
	v_rcp_f32_e32 v102, v102
	v_rcp_f32_e32 v103, v103
	v_pk_add_f32 v[92:93], v[92:93], v[104:105] op_sel:[0,1] neg_lo:[0,1] neg_hi:[0,1]
	v_pk_mul_f32 v[96:97], v[96:97], v[106:107]
	v_pk_mul_f32 v[92:93], v[92:93], v[108:109] op_sel_hi:[1,0]
	v_pk_mul_f32 v[98:99], v[98:99], v[102:103]
	v_pk_fma_f32 v[92:93], v[64:65], v[92:93], v[68:69]
	v_pk_add_f32 v[94:95], v[94:95], v[104:105] op_sel:[0,1] neg_lo:[0,1] neg_hi:[0,1]
	v_mul_f32_e32 v102, 0xbfb8aa3b, v92
	v_exp_f32_e32 v102, v102
	v_mul_f32_e32 v103, 0xbfb8aa3b, v93
	v_exp_f32_e32 v103, v103
	v_cvt_pk_bf16_f32 v96, v96, v97
	v_add_f32_e32 v97, 1.0, v102
	v_pk_mul_f32 v[94:95], v[94:95], v[108:109] op_sel_hi:[1,0]
	v_add_f32_dpp v112, v112, v112 row_mirror row_mask:0xf bank_mask:0xf bound_ctrl:1
	v_rcp_f32_e32 v102, v97
	v_add_f32_e32 v97, 1.0, v103
	v_pk_fma_f32 v[94:95], v[66:67], v[94:95], v[70:71]
	v_add_f32_dpp v113, v113, v113 row_mirror row_mask:0xf bank_mask:0xf bound_ctrl:1
	v_rcp_f32_e32 v103, v97
	v_mul_f32_e32 v97, 0xbfb8aa3b, v94
	v_readlane_b32 s27, v112, 48
	v_exp_f32_e32 v104, v97
	v_cvt_pk_bf16_f32 v97, v98, v99
	v_readlane_b32 s23, v112, 16
	v_mov_b32_e32 v99, s27
	v_readlane_b32 s27, v113, 16
	ds_write2_b64 v122, v[100:101], v[96:97] offset1:66
	v_readlane_b32 s42, v112, 0
	v_readlane_b32 s43, v112, 32
	v_mov_b32_e32 v98, s23
	v_readlane_b32 s23, v113, 0
	v_mov_b32_e32 v100, s27
	v_readlane_b32 s27, v113, 48
	v_pk_add_f32 v[98:99], s[42:43], v[98:99]
	v_add_f32_e32 v100, s23, v100
	v_readlane_b32 s23, v113, 32
	v_mov_b32_e32 v101, s27
	v_pk_mul_f32 v[92:93], v[92:93], v[102:103]
	v_add_f32_e32 v102, s23, v101
	v_mov_b32_e32 v101, v98
	v_mov_b32_e32 v103, v99
	v_pk_add_f32 v[98:99], v[100:101], v[102:103]
	v_mul_f32_e32 v97, 0xbfb8aa3b, v95
	v_pk_mul_f32 v[98:99], v[98:99], s[46:47] op_sel_hi:[1,0]
	v_exp_f32_e32 v97, v97
	v_fma_f32 v100, -v99, v99, v98
	v_max_f32_e32 v100, 0, v100
	v_add_f32_e32 v100, 0x3727c5ac, v100
	v_rsq_f32_e32 v100, v100
	v_pk_add_f32 v[88:89], v[88:89], v[98:99] op_sel:[0,1] neg_lo:[0,1] neg_hi:[0,1]
	v_pk_add_f32 v[90:91], v[90:91], v[98:99] op_sel:[0,1] neg_lo:[0,1] neg_hi:[0,1]
	v_add_f32_e32 v96, 1.0, v104
	v_pk_mul_f32 v[88:89], v[88:89], v[100:101] op_sel_hi:[1,0]
	v_add_f32_e32 v97, 1.0, v97
	v_pk_fma_f32 v[88:89], v[64:65], v[88:89], v[68:69]
	v_rcp_f32_e32 v96, v96
	v_mul_f32_e32 v101, 0xbfb8aa3b, v88
	v_exp_f32_e32 v101, v101
	v_mul_f32_e32 v102, 0xbfb8aa3b, v89
	v_rcp_f32_e32 v97, v97
	v_exp_f32_e32 v102, v102
	v_pk_mul_f32 v[90:91], v[90:91], v[100:101] op_sel_hi:[1,0]
	v_add_f32_dpp v114, v114, v114 quad_perm:[2,3,0,1] row_mask:0xf bank_mask:0xf bound_ctrl:1
	v_pk_fma_f32 v[90:91], v[66:67], v[90:91], v[70:71]
	v_pk_mul_f32 v[94:95], v[94:95], v[96:97]
	v_mul_f32_e32 v98, 0xbfb8aa3b, v90
	v_mul_f32_e32 v99, 0xbfb8aa3b, v91
	v_exp_f32_e32 v98, v98
	v_exp_f32_e32 v99, v99
	v_add_f32_e32 v96, 1.0, v101
	v_add_f32_e32 v97, 1.0, v102
	v_add_f32_dpp v115, v115, v115 quad_perm:[2,3,0,1] row_mask:0xf bank_mask:0xf bound_ctrl:1
	v_add_f32_dpp v114, v114, v114 row_half_mirror row_mask:0xf bank_mask:0xf bound_ctrl:1
	v_rcp_f32_e32 v96, v96
	v_rcp_f32_e32 v97, v97
	v_add_f32_dpp v115, v115, v115 row_half_mirror row_mask:0xf bank_mask:0xf bound_ctrl:1
	v_add_f32_dpp v114, v114, v114 row_mirror row_mask:0xf bank_mask:0xf bound_ctrl:1
	v_add_f32_e32 v98, 1.0, v98
	v_add_f32_e32 v99, 1.0, v99
	v_add_f32_dpp v115, v115, v115 row_mirror row_mask:0xf bank_mask:0xf bound_ctrl:1
	v_rcp_f32_e32 v98, v98
	v_rcp_f32_e32 v99, v99
	v_readlane_b32 s27, v114, 48
	v_cvt_pk_bf16_f32 v92, v92, v93
	v_cvt_pk_bf16_f32 v93, v94, v95
	v_readlane_b32 s23, v114, 16
	v_mov_b32_e32 v95, s27
	v_readlane_b32 s27, v115, 16
	v_pk_mul_f32 v[88:89], v[88:89], v[96:97]
	v_readlane_b32 s42, v114, 0
	v_readlane_b32 s43, v114, 32
	v_mov_b32_e32 v94, s23
	v_readlane_b32 s23, v115, 0
	v_mov_b32_e32 v96, s27
	v_readlane_b32 s27, v115, 48
	v_pk_add_f32 v[94:95], s[42:43], v[94:95]
	v_add_f32_e32 v96, s23, v96
	v_readlane_b32 s23, v115, 32
	v_mov_b32_e32 v97, s27
	v_pk_mul_f32 v[90:91], v[90:91], v[98:99]
	v_add_f32_e32 v98, s23, v97
	v_mov_b32_e32 v97, v94
	v_mov_b32_e32 v99, v95
	v_pk_add_f32 v[94:95], v[96:97], v[98:99]
	v_cvt_pk_bf16_f32 v88, v88, v89
	v_pk_mul_f32 v[94:95], v[94:95], s[46:47] op_sel_hi:[1,0]
	v_cvt_pk_bf16_f32 v89, v90, v91
	v_fma_f32 v96, -v95, v95, v94
	v_max_f32_e32 v96, 0, v96
	v_add_f32_e32 v96, 0x3727c5ac, v96
	v_rsq_f32_e32 v96, v96
	v_pk_add_f32 v[84:85], v[84:85], v[94:95] op_sel:[0,1] neg_lo:[0,1] neg_hi:[0,1]
	v_pk_add_f32 v[86:87], v[86:87], v[94:95] op_sel:[0,1] neg_lo:[0,1] neg_hi:[0,1]
	ds_write2_b64 v122, v[92:93], v[88:89] offset0:132 offset1:198
	v_pk_mul_f32 v[84:85], v[84:85], v[96:97] op_sel_hi:[1,0]
	v_pk_mul_f32 v[86:87], v[86:87], v[96:97] op_sel_hi:[1,0]
	v_pk_fma_f32 v[84:85], v[64:65], v[84:85], v[68:69]
	v_pk_fma_f32 v[86:87], v[66:67], v[86:87], v[70:71]
	v_mul_f32_e32 v90, 0xbfb8aa3b, v84
	v_mul_f32_e32 v91, 0xbfb8aa3b, v85
	v_exp_f32_e32 v90, v90
	v_exp_f32_e32 v91, v91
	v_add_f32_dpp v116, v116, v116 quad_perm:[2,3,0,1] row_mask:0xf bank_mask:0xf bound_ctrl:1
	v_add_f32_dpp v117, v117, v117 quad_perm:[2,3,0,1] row_mask:0xf bank_mask:0xf bound_ctrl:1
	v_add_f32_e32 v88, 1.0, v90
	v_add_f32_e32 v89, 1.0, v91
	v_mul_f32_e32 v91, 0xbfb8aa3b, v87
	v_rcp_f32_e32 v88, v88
	v_rcp_f32_e32 v89, v89
	v_mul_f32_e32 v90, 0xbfb8aa3b, v86
	v_exp_f32_e32 v91, v91
	v_add_f32_dpp v116, v116, v116 row_half_mirror row_mask:0xf bank_mask:0xf bound_ctrl:1
	v_exp_f32_e32 v90, v90
	v_add_f32_dpp v117, v117, v117 row_half_mirror row_mask:0xf bank_mask:0xf bound_ctrl:1
	v_add_f32_dpp v116, v116, v116 row_mirror row_mask:0xf bank_mask:0xf bound_ctrl:1
	v_pk_mul_f32 v[84:85], v[84:85], v[88:89]
	v_add_f32_dpp v117, v117, v117 row_mirror row_mask:0xf bank_mask:0xf bound_ctrl:1
	v_readlane_b32 s27, v116, 48
	v_add_f32_e32 v89, 1.0, v91
	v_readlane_b32 s23, v116, 16
	v_mov_b32_e32 v91, s27
	v_readlane_b32 s27, v117, 16
	v_add_f32_e32 v88, 1.0, v90
	v_readlane_b32 s42, v116, 0
	v_readlane_b32 s43, v116, 32
	v_mov_b32_e32 v90, s23
	v_readlane_b32 s23, v117, 0
	v_mov_b32_e32 v92, s27
	v_readlane_b32 s27, v117, 48
	v_pk_add_f32 v[90:91], s[42:43], v[90:91]
	v_add_f32_e32 v92, s23, v92
	v_readlane_b32 s23, v117, 32
	v_mov_b32_e32 v93, s27
	v_mov_b32_e32 v95, v91
	v_add_f32_e32 v94, s23, v93
	v_mov_b32_e32 v93, v90
	v_pk_add_f32 v[90:91], v[92:93], v[94:95]
	v_rcp_f32_e32 v88, v88
	v_pk_mul_f32 v[90:91], v[90:91], s[46:47] op_sel_hi:[1,0]
	v_rcp_f32_e32 v89, v89
	v_fma_f32 v92, -v91, v91, v90
	v_max_f32_e32 v92, 0, v92
	v_add_f32_e32 v92, 0x3727c5ac, v92
	v_rsq_f32_e32 v92, v92
	v_pk_add_f32 v[80:81], v[80:81], v[90:91] op_sel:[0,1] neg_lo:[0,1] neg_hi:[0,1]
	v_cvt_pk_bf16_f32 v84, v84, v85
	v_pk_mul_f32 v[86:87], v[86:87], v[88:89]
	v_pk_mul_f32 v[80:81], v[80:81], v[92:93] op_sel_hi:[1,0]
	v_pk_add_f32 v[82:83], v[82:83], v[90:91] op_sel:[0,1] neg_lo:[0,1] neg_hi:[0,1]
	v_pk_fma_f32 v[80:81], v[64:65], v[80:81], v[68:69]
	v_pk_mul_f32 v[82:83], v[82:83], v[92:93] op_sel_hi:[1,0]
	v_mul_f32_e32 v85, 0xbfb8aa3b, v80
	v_exp_f32_e32 v88, v85
	v_mul_f32_e32 v85, 0xbfb8aa3b, v81
	v_exp_f32_e32 v89, v85
	v_pk_fma_f32 v[82:83], v[66:67], v[82:83], v[70:71]
	v_cvt_pk_bf16_f32 v85, v86, v87
	v_add_f32_e32 v86, 1.0, v88
	v_add_f32_e32 v87, 1.0, v89
	v_mul_f32_e32 v89, 0xbfb8aa3b, v83
	v_add_f32_dpp v118, v118, v118 quad_perm:[2,3,0,1] row_mask:0xf bank_mask:0xf bound_ctrl:1
	v_rcp_f32_e32 v86, v86
	v_rcp_f32_e32 v87, v87
	v_mul_f32_e32 v88, 0xbfb8aa3b, v82
	v_exp_f32_e32 v89, v89
	v_add_f32_dpp v119, v119, v119 quad_perm:[2,3,0,1] row_mask:0xf bank_mask:0xf bound_ctrl:1
	v_add_f32_dpp v118, v118, v118 row_half_mirror row_mask:0xf bank_mask:0xf bound_ctrl:1
	v_exp_f32_e32 v88, v88
	v_add_f32_dpp v119, v119, v119 row_half_mirror row_mask:0xf bank_mask:0xf bound_ctrl:1
	v_add_f32_dpp v118, v118, v118 row_mirror row_mask:0xf bank_mask:0xf bound_ctrl:1
	v_pk_mul_f32 v[80:81], v[80:81], v[86:87]
	v_add_f32_dpp v119, v119, v119 row_mirror row_mask:0xf bank_mask:0xf bound_ctrl:1
	v_readlane_b32 s27, v118, 48
	v_add_f32_e32 v87, 1.0, v89
	v_readlane_b32 s23, v118, 16
	v_mov_b32_e32 v89, s27
	v_readlane_b32 s27, v119, 16
	v_add_f32_e32 v86, 1.0, v88
	v_readlane_b32 s42, v118, 0
	v_readlane_b32 s43, v118, 32
	v_mov_b32_e32 v88, s23
	v_readlane_b32 s23, v119, 0
	v_mov_b32_e32 v90, s27
	v_readlane_b32 s27, v119, 48
	v_pk_add_f32 v[88:89], s[42:43], v[88:89]
	v_add_f32_e32 v90, s23, v90
	v_readlane_b32 s23, v119, 32
	v_mov_b32_e32 v91, s27
	v_mov_b32_e32 v93, v89
	v_add_f32_e32 v92, s23, v91
	v_mov_b32_e32 v91, v88
	v_pk_add_f32 v[88:89], v[90:91], v[92:93]
	v_rcp_f32_e32 v86, v86
	v_pk_mul_f32 v[88:89], v[88:89], s[46:47] op_sel_hi:[1,0]
	v_rcp_f32_e32 v87, v87
	v_fma_f32 v90, -v89, v89, v88
	v_max_f32_e32 v90, 0, v90
	v_add_f32_e32 v90, 0x3727c5ac, v90
	v_rsq_f32_e32 v90, v90
	v_pk_add_f32 v[76:77], v[76:77], v[88:89] op_sel:[0,1] neg_lo:[0,1] neg_hi:[0,1]
	v_cvt_pk_bf16_f32 v80, v80, v81
	v_pk_mul_f32 v[82:83], v[82:83], v[86:87]
	v_pk_mul_f32 v[76:77], v[76:77], v[90:91] op_sel_hi:[1,0]
	v_pk_add_f32 v[78:79], v[78:79], v[88:89] op_sel:[0,1] neg_lo:[0,1] neg_hi:[0,1]
	v_pk_fma_f32 v[76:77], v[64:65], v[76:77], v[68:69]
	v_add_f32_dpp v120, v120, v120 quad_perm:[2,3,0,1] row_mask:0xf bank_mask:0xf bound_ctrl:1
	v_mul_f32_e32 v81, 0xbfb8aa3b, v76
	v_exp_f32_e32 v86, v81
	v_mul_f32_e32 v81, 0xbfb8aa3b, v77
	v_exp_f32_e32 v87, v81
	v_cvt_pk_bf16_f32 v81, v82, v83
	v_add_f32_e32 v82, 1.0, v86
	v_rcp_f32_e32 v82, v82
	v_add_f32_e32 v83, 1.0, v87
	v_rcp_f32_e32 v83, v83
	v_pk_mul_f32 v[78:79], v[78:79], v[90:91] op_sel_hi:[1,0]
	v_add_f32_dpp v120, v120, v120 row_half_mirror row_mask:0xf bank_mask:0xf bound_ctrl:1
	v_pk_fma_f32 v[78:79], v[66:67], v[78:79], v[70:71]
	v_add_f32_dpp v121, v121, v121 row_mirror row_mask:0xf bank_mask:0xf bound_ctrl:1
	v_add_f32_dpp v120, v120, v120 row_mirror row_mask:0xf bank_mask:0xf bound_ctrl:1
	v_mul_f32_e32 v86, 0xbfb8aa3b, v78
	v_exp_f32_e32 v86, v86
	v_readlane_b32 s27, v120, 48
	v_add_u32_e32 v88, 0x800, v122
	v_pk_mul_f32 v[76:77], v[76:77], v[82:83]
	v_readlane_b32 s23, v120, 16
	v_mov_b32_e32 v83, s27
	v_readlane_b32 s27, v121, 16
	ds_write2_b64 v88, v[84:85], v[80:81] offset0:8 offset1:74
	v_readlane_b32 s42, v120, 0
	v_readlane_b32 s43, v120, 32
	v_mov_b32_e32 v82, s23
	v_readlane_b32 s23, v121, 0
	v_mov_b32_e32 v84, s27
	v_readlane_b32 s27, v121, 48
	v_pk_add_f32 v[82:83], s[42:43], v[82:83]
	v_add_f32_e32 v84, s23, v84
	v_readlane_b32 s23, v121, 32
	v_mov_b32_e32 v85, s27
	v_add_f32_e32 v80, 1.0, v86
	v_add_f32_e32 v86, s23, v85
	v_mov_b32_e32 v85, v82
	v_mov_b32_e32 v87, v83
	v_pk_add_f32 v[82:83], v[84:85], v[86:87]
	v_mul_f32_e32 v81, 0xbfb8aa3b, v79
	v_pk_mul_f32 v[82:83], v[82:83], s[46:47] op_sel_hi:[1,0]
	v_exp_f32_e32 v81, v81
	v_fma_f32 v84, -v83, v83, v82
	v_max_f32_e32 v84, 0, v84
	v_add_f32_e32 v84, 0x3727c5ac, v84
	v_rsq_f32_e32 v84, v84
	v_pk_add_f32 v[72:73], v[72:73], v[82:83] op_sel:[0,1] neg_lo:[0,1] neg_hi:[0,1]
	v_pk_add_f32 v[74:75], v[74:75], v[82:83] op_sel:[0,1] neg_lo:[0,1] neg_hi:[0,1]
	v_add_f32_e32 v81, 1.0, v81
	v_pk_mul_f32 v[72:73], v[72:73], v[84:85] op_sel_hi:[1,0]
	v_pk_mul_f32 v[74:75], v[74:75], v[84:85] op_sel_hi:[1,0]
	v_pk_fma_f32 v[64:65], v[64:65], v[72:73], v[68:69]
	v_pk_fma_f32 v[66:67], v[66:67], v[74:75], v[70:71]
	v_mul_f32_e32 v68, 0xbfb8aa3b, v64
	v_exp_f32_e32 v72, v68
	v_mul_f32_e32 v68, 0xbfb8aa3b, v65
	v_mul_f32_e32 v70, 0xbfb8aa3b, v66
	v_mul_f32_e32 v71, 0xbfb8aa3b, v67
	v_exp_f32_e32 v73, v68
	v_exp_f32_e32 v70, v70
	v_exp_f32_e32 v71, v71
	v_add_f32_e32 v72, 1.0, v72
	v_add_f32_e32 v73, 1.0, v73
	v_add_f32_e32 v70, 1.0, v70
	v_add_f32_e32 v71, 1.0, v71
	v_rcp_f32_e32 v80, v80
	v_rcp_f32_e32 v81, v81
	v_rcp_f32_e32 v72, v72
	v_rcp_f32_e32 v73, v73
	v_rcp_f32_e32 v70, v70
	v_rcp_f32_e32 v71, v71
	v_pk_mul_f32 v[68:69], v[78:79], v[80:81]
	v_pk_mul_f32 v[64:65], v[64:65], v[72:73]
	v_cvt_pk_bf16_f32 v74, v76, v77
	v_pk_mul_f32 v[66:67], v[66:67], v[70:71]
	v_cvt_pk_bf16_f32 v75, v68, v69
	v_cvt_pk_bf16_f32 v64, v64, v65
	v_cvt_pk_bf16_f32 v65, v66, v67
	ds_write2_b64 v88, v[74:75], v[64:65] offset0:140 offset1:206
	v_mul_u32_u24_e32 v64, 0x210, v158
	v_add3_u32 v108, 0, v148, v64
	s_waitcnt lgkmcnt(0)
	s_barrier
	ds_read_b128 v[64:67], v108
	ds_read_b128 v[68:71], v108 offset:64
	ds_read_b128 v[76:79], v108 offset:8448
	ds_read_b128 v[80:83], v108 offset:8512
	ds_read_b128 v[88:91], v108 offset:16896
	ds_read_b128 v[92:95], v108 offset:16960
	ds_read_b128 v[100:103], v108 offset:25344
	ds_read_b128 v[104:107], v108 offset:25408
	ds_read_b128 v[110:113], v108 offset:128
	ds_read_b128 v[114:117], v108 offset:192
	ds_read_b128 v[118:121], v108 offset:8576
	ds_read_b128 v[122:125], v108 offset:8640
	ds_read_b128 v[126:129], v108 offset:17024
	ds_read_b128 v[130:133], v108 offset:17088
	ds_read_b128 v[134:137], v108 offset:25472
	s_waitcnt lgkmcnt(14)
	ds_read_b128 v[138:141], v108 offset:25536
	v_mfma_f32_16x16x32_bf16 v[72:75], v[64:67], v[56:59], 0
	v_readlane_b32 s23, v254, 36
	v_mfma_f32_16x16x32_bf16 v[64:67], v[64:67], v[60:63], 0
	s_waitcnt lgkmcnt(13)
	ds_read_b128 v[142:145], v108 offset:256
	ds_read_b128 v[162:165], v108 offset:320
	v_mfma_f32_16x16x32_bf16 v[84:87], v[76:79], v[56:59], 0
	v_mfma_f32_16x16x32_bf16 v[76:79], v[76:79], v[60:63], 0
	s_waitcnt lgkmcnt(13)
	ds_read_b128 v[166:169], v108 offset:8704
	ds_read_b128 v[170:173], v108 offset:8768
	v_mfma_f32_16x16x32_bf16 v[96:99], v[88:91], v[56:59], 0
	v_mfma_f32_16x16x32_bf16 v[88:91], v[88:91], v[60:63], 0
	s_waitcnt lgkmcnt(13)
	ds_read_b128 v[174:177], v108 offset:17152
	ds_read_b128 v[178:181], v108 offset:17216
	v_mfma_f32_16x16x32_bf16 v[56:59], v[100:103], v[56:59], 0
	v_mfma_f32_16x16x32_bf16 v[60:63], v[100:103], v[60:63], 0
	v_mfma_f32_16x16x32_bf16 v[72:75], v[68:71], v[48:51], v[72:75]
	v_mfma_f32_16x16x32_bf16 v[64:67], v[68:71], v[52:55], v[64:67]
	v_mfma_f32_16x16x32_bf16 v[68:71], v[80:83], v[48:51], v[84:87]
	v_mfma_f32_16x16x32_bf16 v[76:79], v[80:83], v[52:55], v[76:79]
	v_mfma_f32_16x16x32_bf16 v[80:83], v[92:95], v[48:51], v[96:99]
	v_mfma_f32_16x16x32_bf16 v[84:87], v[92:95], v[52:55], v[88:91]
	s_waitcnt lgkmcnt(14)
	ds_read_b128 v[182:185], v108 offset:25600
	v_mfma_f32_16x16x32_bf16 v[48:51], v[104:107], v[48:51], v[56:59]
	v_mfma_f32_16x16x32_bf16 v[52:55], v[104:107], v[52:55], v[60:63]
	s_nop 1
	s_waitcnt lgkmcnt(14)
	ds_read_b128 v[186:189], v108 offset:25664
	v_mfma_f32_16x16x32_bf16 v[72:75], v[110:113], v[40:43], v[72:75]
	v_mfma_f32_16x16x32_bf16 v[56:59], v[110:113], v[44:47], v[64:67]
	s_nop 2
	s_waitcnt lgkmcnt(13)
	ds_read_b128 v[190:193], v108 offset:384
	ds_read_b128 v[194:197], v108 offset:448
	v_mfma_f32_16x16x32_bf16 v[68:71], v[118:121], v[40:43], v[68:71]
	v_mfma_f32_16x16x32_bf16 v[64:67], v[118:121], v[44:47], v[76:79]
	s_nop 2
	s_waitcnt lgkmcnt(13)
	ds_read_b128 v[198:201], v108 offset:8832
	ds_read_b128 v[202:205], v108 offset:8896
	v_mfma_f32_16x16x32_bf16 v[80:83], v[126:129], v[40:43], v[80:83]
	v_mfma_f32_16x16x32_bf16 v[76:79], v[126:129], v[44:47], v[84:87]
	s_nop 2
	s_waitcnt lgkmcnt(13)
	ds_read_b128 v[206:209], v108 offset:17280
	ds_read_b128 v[218:221], v108 offset:17344
	v_mfma_f32_16x16x32_bf16 v[40:43], v[134:137], v[40:43], v[48:51]
	v_mfma_f32_16x16x32_bf16 v[44:47], v[134:137], v[44:47], v[52:55]
	v_mfma_f32_16x16x32_bf16 v[48:51], v[114:117], v[32:35], v[72:75]
	v_mfma_f32_16x16x32_bf16 v[52:55], v[114:117], v[36:39], v[56:59]
	v_mfma_f32_16x16x32_bf16 v[56:59], v[122:125], v[32:35], v[68:71]
	v_mfma_f32_16x16x32_bf16 v[60:63], v[122:125], v[36:39], v[64:67]
	v_mfma_f32_16x16x32_bf16 v[64:67], v[130:133], v[32:35], v[80:83]
	v_mfma_f32_16x16x32_bf16 v[68:71], v[130:133], v[36:39], v[76:79]
	s_waitcnt lgkmcnt(14)
	ds_read_b128 v[222:225], v108 offset:25728
	v_mfma_f32_16x16x32_bf16 v[32:35], v[138:141], v[32:35], v[40:43]
	v_mfma_f32_16x16x32_bf16 v[36:39], v[138:141], v[36:39], v[44:47]
	s_nop 1
	s_waitcnt lgkmcnt(14)
	ds_read_b128 v[226:229], v108 offset:25792
	v_mfma_f32_16x16x32_bf16 v[48:51], v[142:145], v[24:27], v[48:51]
	v_mfma_f32_16x16x32_bf16 v[40:43], v[142:145], v[28:31], v[52:55]
	s_nop 2
	s_waitcnt lgkmcnt(13)
	v_mfma_f32_16x16x32_bf16 v[56:59], v[166:169], v[24:27], v[56:59]
	v_mfma_f32_16x16x32_bf16 v[52:55], v[166:169], v[28:31], v[60:63]
	s_nop 2
	s_waitcnt lgkmcnt(11)
	v_mfma_f32_16x16x32_bf16 v[64:67], v[174:177], v[24:27], v[64:67]
	v_mfma_f32_16x16x32_bf16 v[60:63], v[174:177], v[28:31], v[68:71]
	s_nop 2
	s_waitcnt lgkmcnt(9)
	v_mfma_f32_16x16x32_bf16 v[24:27], v[182:185], v[24:27], v[32:35]
	v_mfma_f32_16x16x32_bf16 v[28:31], v[182:185], v[28:31], v[36:39]
	v_mfma_f32_16x16x32_bf16 v[32:35], v[162:165], v[16:19], v[48:51]
	v_mfma_f32_16x16x32_bf16 v[36:39], v[162:165], v[20:23], v[40:43]
	v_mfma_f32_16x16x32_bf16 v[40:43], v[170:173], v[16:19], v[56:59]
	v_mfma_f32_16x16x32_bf16 v[44:47], v[170:173], v[20:23], v[52:55]
	v_mfma_f32_16x16x32_bf16 v[48:51], v[178:181], v[16:19], v[64:67]
	v_mfma_f32_16x16x32_bf16 v[52:55], v[178:181], v[20:23], v[60:63]
	s_waitcnt lgkmcnt(8)
	v_mfma_f32_16x16x32_bf16 v[16:19], v[186:189], v[16:19], v[24:27]
	v_mfma_f32_16x16x32_bf16 v[20:23], v[186:189], v[20:23], v[28:31]
	s_nop 1
	s_waitcnt lgkmcnt(7)
	v_mfma_f32_16x16x32_bf16 v[32:35], v[190:193], v[8:11], v[32:35]
	v_mfma_f32_16x16x32_bf16 v[24:27], v[190:193], v[12:15], v[36:39]
	s_nop 2
	s_waitcnt lgkmcnt(5)
	v_mfma_f32_16x16x32_bf16 v[40:43], v[198:201], v[8:11], v[40:43]
	v_mfma_f32_16x16x32_bf16 v[36:39], v[198:201], v[12:15], v[44:47]
	s_nop 2
	s_waitcnt lgkmcnt(3)
	v_mfma_f32_16x16x32_bf16 v[48:51], v[206:209], v[8:11], v[48:51]
	v_mfma_f32_16x16x32_bf16 v[44:47], v[206:209], v[12:15], v[52:55]
	s_nop 2
	s_waitcnt lgkmcnt(1)
	v_mfma_f32_16x16x32_bf16 v[68:71], v[222:225], v[8:11], v[16:19]
	v_mfma_f32_16x16x32_bf16 v[32:35], v[194:197], v[4:7], v[32:35]
	v_mfma_f32_16x16x32_bf16 v[16:19], v[194:197], v[0:3], v[24:27]
	v_or_b32_e32 v28, s26, v158
	v_lshlrev_b32_e32 v29, 7, v156
	v_and_b32_e32 v29, 0x1800, v29
	v_lshlrev_b32_e32 v28, 1, v28
	v_add3_u32 v30, s23, v28, v29
	v_mfma_f32_16x16x32_bf16 v[52:55], v[222:225], v[12:15], v[20:23]
	v_readlane_b32 s26, v254, 37
	v_mfma_f32_16x16x32_bf16 v[24:27], v[202:205], v[4:7], v[40:43]
	v_mfma_f32_16x16x32_bf16 v[12:15], v[202:205], v[0:3], v[36:39]
	ds_read_u16 v31, v30
	s_nop 1
	ds_read_u16 v36, v30 offset:512
	ds_read_u16 v37, v30 offset:1024
	ds_read_u16 v38, v30 offset:1536
	ds_read_u16 v39, v30 offset:8192
	ds_read_u16 v40, v30 offset:8704
	ds_read_u16 v41, v30 offset:9216
	ds_read_u16 v42, v30 offset:9728
	s_waitcnt lgkmcnt(7)
	v_lshlrev_b32_e32 v31, 16, v31
	v_mul_f32_e32 v43, 0xbfb8aa3b, v31
	v_exp_f32_e32 v43, v43
	s_waitcnt lgkmcnt(6)
	v_lshlrev_b32_e32 v36, 16, v36
	v_mfma_f32_16x16x32_bf16 v[8:11], v[218:221], v[0:3], v[44:47]
	s_waitcnt lgkmcnt(5)
	v_lshlrev_b32_e32 v37, 16, v37
	v_add_f32_e32 v43, 1.0, v43
	v_rcp_f32_e32 v43, v43
	v_mul_f32_e32 v44, 0xbfb8aa3b, v36
	v_exp_f32_e32 v44, v44
	v_mfma_f32_16x16x32_bf16 v[20:23], v[218:221], v[4:7], v[48:51]
	v_mul_f32_e32 v31, v43, v31
	v_mul_f32_e32 v31, v32, v31
	v_add_f32_e32 v32, 1.0, v44
	v_rcp_f32_e32 v32, v32
	v_mul_f32_e32 v43, 0xbfb8aa3b, v37
	v_exp_f32_e32 v43, v43
	v_cvt_pk_bf16_f32 v31, v31, s0
	ds_write_b16 v30, v31
	v_mul_f32_e32 v31, v32, v36
	v_mul_f32_e32 v31, v33, v31
	s_waitcnt lgkmcnt(5)
	v_lshlrev_b32_e32 v33, 16, v38
	v_add_f32_e32 v32, 1.0, v43
	v_mul_f32_e32 v36, 0xbfb8aa3b, v33
	v_rcp_f32_e32 v32, v32
	v_exp_f32_e32 v36, v36
	v_cvt_pk_bf16_f32 v31, v31, s0
	ds_write_b16 v30, v31 offset:512
	v_mul_f32_e32 v31, v32, v37
	v_add_f32_e32 v32, 1.0, v36
	v_rcp_f32_e32 v32, v32
	v_mul_f32_e32 v31, v34, v31
	v_cvt_pk_bf16_f32 v31, v31, s0
	ds_write_b16 v30, v31 offset:1024
	v_mul_f32_e32 v31, v32, v33
	s_waitcnt lgkmcnt(6)
	v_lshlrev_b32_e32 v32, 16, v39
	v_mul_f32_e32 v33, 0xbfb8aa3b, v32
	v_exp_f32_e32 v33, v33
	v_mul_f32_e32 v31, v35, v31
	v_cvt_pk_bf16_f32 v31, v31, s0
	ds_write_b16 v30, v31 offset:1536
	v_add_f32_e32 v31, 1.0, v33
	s_waitcnt lgkmcnt(6)
	v_lshlrev_b32_e32 v33, 16, v40
	v_rcp_f32_e32 v31, v31
	v_mul_f32_e32 v34, 0xbfb8aa3b, v33
	v_exp_f32_e32 v34, v34
	v_mfma_f32_16x16x32_bf16 v[4:7], v[226:229], v[4:7], v[68:71]
	v_mul_f32_e32 v31, v31, v32
	v_mul_f32_e32 v24, v24, v31
	v_add_f32_e32 v31, 1.0, v34
	s_waitcnt lgkmcnt(5)
	v_lshlrev_b32_e32 v32, 16, v41
	v_rcp_f32_e32 v31, v31
	v_mul_f32_e32 v34, 0xbfb8aa3b, v32
	v_exp_f32_e32 v34, v34
	v_cvt_pk_bf16_f32 v24, v24, s0
	ds_write_b16 v30, v24 offset:8192
	v_mul_f32_e32 v24, v31, v33
	s_waitcnt lgkmcnt(5)
	v_lshlrev_b32_e32 v31, 16, v42
	v_mul_f32_e32 v24, v25, v24
	v_add_f32_e32 v25, 1.0, v34
	v_mul_f32_e32 v33, 0xbfb8aa3b, v31
	v_rcp_f32_e32 v25, v25
	v_exp_f32_e32 v33, v33
	v_cvt_pk_bf16_f32 v24, v24, s0
	ds_write_b16 v30, v24 offset:8704
	v_mul_f32_e32 v24, v25, v32
	v_add_f32_e32 v25, 1.0, v33
	v_rcp_f32_e32 v25, v25
	v_mul_f32_e32 v24, v26, v24
	v_cvt_pk_bf16_f32 v24, v24, s0
	ds_write_b16 v30, v24 offset:9216
	v_mul_f32_e32 v24, v25, v31
	ds_read_u16 v25, v30 offset:16384
	ds_read_u16 v26, v30 offset:16896
	ds_read_u16 v31, v30 offset:17408
	ds_read_u16 v32, v30 offset:17920
	ds_read_u16 v33, v30 offset:24576
	ds_read_u16 v34, v30 offset:25088
	ds_read_u16 v35, v30 offset:25600
	ds_read_u16 v36, v30 offset:26112
	s_waitcnt lgkmcnt(7)
	v_lshlrev_b32_e32 v25, 16, v25
	v_mul_f32_e32 v37, 0xbfb8aa3b, v25
	v_exp_f32_e32 v37, v37
	v_mul_f32_e32 v24, v27, v24
	v_cvt_pk_bf16_f32 v24, v24, s0
	ds_write_b16 v30, v24 offset:9728
	v_add_f32_e32 v24, 1.0, v37
	s_waitcnt lgkmcnt(7)
	v_lshlrev_b32_e32 v26, 16, v26
	v_rcp_f32_e32 v24, v24
	v_mul_f32_e32 v27, 0xbfb8aa3b, v26
	v_exp_f32_e32 v27, v27
	v_mfma_f32_16x16x32_bf16 v[0:3], v[226:229], v[0:3], v[52:55]
	v_mul_f32_e32 v24, v24, v25
	v_mul_f32_e32 v20, v20, v24
	v_add_f32_e32 v24, 1.0, v27
	s_waitcnt lgkmcnt(6)
	v_lshlrev_b32_e32 v25, 16, v31
	v_rcp_f32_e32 v24, v24
	v_mul_f32_e32 v27, 0xbfb8aa3b, v25
	v_exp_f32_e32 v27, v27
	v_cvt_pk_bf16_f32 v20, v20, s0
	ds_write_b16 v30, v20 offset:16384
	v_mul_f32_e32 v20, v24, v26
	s_waitcnt lgkmcnt(6)
	v_lshlrev_b32_e32 v24, 16, v32
	v_mul_f32_e32 v20, v21, v20
	v_add_f32_e32 v21, 1.0, v27
	v_mul_f32_e32 v26, 0xbfb8aa3b, v24
	v_rcp_f32_e32 v21, v21
	v_exp_f32_e32 v26, v26
	v_cvt_pk_bf16_f32 v20, v20, s0
	ds_write_b16 v30, v20 offset:16896
	v_mul_f32_e32 v20, v21, v25
	v_add_f32_e32 v21, 1.0, v26
	v_rcp_f32_e32 v21, v21
	v_mul_f32_e32 v20, v22, v20
	v_cvt_pk_bf16_f32 v20, v20, s0
	ds_write_b16 v30, v20 offset:17408
	v_mul_f32_e32 v20, v21, v24
	s_waitcnt lgkmcnt(7)
	v_lshlrev_b32_e32 v21, 16, v33
	v_mul_f32_e32 v22, 0xbfb8aa3b, v21
	v_exp_f32_e32 v22, v22
	v_mul_f32_e32 v20, v23, v20
	v_cvt_pk_bf16_f32 v20, v20, s0
	ds_write_b16 v30, v20 offset:17920
	v_add_f32_e32 v20, 1.0, v22
	s_waitcnt lgkmcnt(7)
	v_lshlrev_b32_e32 v22, 16, v34
	v_rcp_f32_e32 v20, v20
	v_mul_f32_e32 v23, 0xbfb8aa3b, v22
	v_exp_f32_e32 v23, v23
	v_mul_f32_e32 v20, v20, v21
	v_mul_f32_e32 v4, v4, v20
	v_add_f32_e32 v20, 1.0, v23
	s_waitcnt lgkmcnt(6)
	v_lshlrev_b32_e32 v21, 16, v35
	v_rcp_f32_e32 v20, v20
	v_mul_f32_e32 v23, 0xbfb8aa3b, v21
	v_exp_f32_e32 v23, v23
	v_cvt_pk_bf16_f32 v4, v4, s0
	ds_write_b16 v30, v4 offset:24576
	v_mul_f32_e32 v4, v20, v22
	s_waitcnt lgkmcnt(6)
	v_lshlrev_b32_e32 v20, 16, v36
	v_mul_f32_e32 v4, v5, v4
	v_add_f32_e32 v5, 1.0, v23
	v_mul_f32_e32 v22, 0xbfb8aa3b, v20
	v_rcp_f32_e32 v5, v5
	v_exp_f32_e32 v22, v22
	v_cvt_pk_bf16_f32 v4, v4, s0
	ds_write_b16 v30, v4 offset:25088
	v_mul_f32_e32 v4, v5, v21
	v_add_f32_e32 v5, 1.0, v22
	v_rcp_f32_e32 v5, v5
	v_mul_f32_e32 v4, v6, v4
	v_cvt_pk_bf16_f32 v4, v4, s0
	ds_write_b16 v30, v4 offset:25600
	v_mul_f32_e32 v4, v5, v20
	v_add3_u32 v5, s26, v28, v29
	ds_read_u16 v6, v5
	ds_read_u16 v20, v5 offset:512
	ds_read_u16 v21, v5 offset:1024
	ds_read_u16 v22, v5 offset:1536
	ds_read_u16 v23, v5 offset:8192
	ds_read_u16 v24, v5 offset:8704
	ds_read_u16 v25, v5 offset:9216
	ds_read_u16 v26, v5 offset:9728
	s_waitcnt lgkmcnt(7)
	v_lshlrev_b32_e32 v6, 16, v6
	v_mul_f32_e32 v27, 0xbfb8aa3b, v6
	v_exp_f32_e32 v27, v27
	v_mul_f32_e32 v4, v7, v4
	v_cvt_pk_bf16_f32 v4, v4, s0
	ds_write_b16 v30, v4 offset:26112
	v_add_f32_e32 v4, 1.0, v27
	s_waitcnt lgkmcnt(7)
	v_lshlrev_b32_e32 v7, 16, v20
	v_rcp_f32_e32 v4, v4
	v_mul_f32_e32 v20, 0xbfb8aa3b, v7
	v_exp_f32_e32 v20, v20
	v_readlane_b32 s26, v255, 9
	v_mul_f32_e32 v4, v4, v6
	v_mul_f32_e32 v4, v16, v4
	v_add_f32_e32 v6, 1.0, v20
	s_waitcnt lgkmcnt(6)
	v_lshlrev_b32_e32 v16, 16, v21
	v_rcp_f32_e32 v6, v6
	v_mul_f32_e32 v20, 0xbfb8aa3b, v16
	v_exp_f32_e32 v20, v20
	v_cvt_pk_bf16_f32 v4, v4, s0
	ds_write_b16 v5, v4
	v_mul_f32_e32 v4, v6, v7
	s_waitcnt lgkmcnt(6)
	v_lshlrev_b32_e32 v7, 16, v22
	v_mul_f32_e32 v4, v17, v4
	v_add_f32_e32 v6, 1.0, v20
	v_mul_f32_e32 v17, 0xbfb8aa3b, v7
	v_rcp_f32_e32 v6, v6
	v_exp_f32_e32 v17, v17
	v_cvt_pk_bf16_f32 v4, v4, s0
	ds_write_b16 v5, v4 offset:512
	v_mul_f32_e32 v4, v6, v16
	v_add_f32_e32 v6, 1.0, v17
	v_rcp_f32_e32 v6, v6
	v_mul_f32_e32 v4, v18, v4
	v_cvt_pk_bf16_f32 v4, v4, s0
	ds_write_b16 v5, v4 offset:1024
	v_mul_f32_e32 v4, v6, v7
	s_waitcnt lgkmcnt(7)
	v_lshlrev_b32_e32 v6, 16, v23
	v_mul_f32_e32 v7, 0xbfb8aa3b, v6
	v_exp_f32_e32 v7, v7
	v_mul_f32_e32 v4, v19, v4
	v_cvt_pk_bf16_f32 v4, v4, s0
	ds_write_b16 v5, v4 offset:1536
	v_add_f32_e32 v4, 1.0, v7
	s_waitcnt lgkmcnt(7)
	v_lshlrev_b32_e32 v7, 16, v24
	v_rcp_f32_e32 v4, v4
	v_mul_f32_e32 v16, 0xbfb8aa3b, v7
	v_exp_f32_e32 v16, v16
	v_readlane_b32 s27, v255, 10
	v_mul_f32_e32 v4, v4, v6
	v_mul_f32_e32 v4, v12, v4
	v_add_f32_e32 v6, 1.0, v16
	s_waitcnt lgkmcnt(6)
	v_lshlrev_b32_e32 v12, 16, v25
	v_rcp_f32_e32 v6, v6
	v_mul_f32_e32 v16, 0xbfb8aa3b, v12
	v_exp_f32_e32 v16, v16
	v_cvt_pk_bf16_f32 v4, v4, s0
	ds_write_b16 v5, v4 offset:8192
	v_mul_f32_e32 v4, v6, v7
	s_waitcnt lgkmcnt(6)
	v_lshlrev_b32_e32 v7, 16, v26
	v_mul_f32_e32 v4, v13, v4
	v_add_f32_e32 v6, 1.0, v16
	v_mul_f32_e32 v13, 0xbfb8aa3b, v7
	v_rcp_f32_e32 v6, v6
	v_exp_f32_e32 v13, v13
	v_cvt_pk_bf16_f32 v4, v4, s0
	ds_write_b16 v5, v4 offset:8704
	v_mul_f32_e32 v4, v6, v12
	v_add_f32_e32 v6, 1.0, v13
	v_rcp_f32_e32 v6, v6
	v_mul_f32_e32 v4, v14, v4
	v_cvt_pk_bf16_f32 v4, v4, s0
	ds_write_b16 v5, v4 offset:9216
	v_mul_f32_e32 v4, v6, v7
	ds_read_u16 v6, v5 offset:16384
	ds_read_u16 v7, v5 offset:16896
	ds_read_u16 v12, v5 offset:17408
	ds_read_u16 v13, v5 offset:17920
	ds_read_u16 v14, v5 offset:24576
	ds_read_u16 v16, v5 offset:25088
	ds_read_u16 v17, v5 offset:25600
	ds_read_u16 v18, v5 offset:26112
	s_waitcnt lgkmcnt(7)
	v_lshlrev_b32_e32 v6, 16, v6
	v_mul_f32_e32 v19, 0xbfb8aa3b, v6
	v_exp_f32_e32 v19, v19
	v_mul_f32_e32 v4, v15, v4
	v_cvt_pk_bf16_f32 v4, v4, s0
	ds_write_b16 v5, v4 offset:9728
	v_add_f32_e32 v4, 1.0, v19
	s_waitcnt lgkmcnt(7)
	v_lshlrev_b32_e32 v7, 16, v7
	v_rcp_f32_e32 v4, v4
	v_mul_f32_e32 v15, 0xbfb8aa3b, v7
	v_exp_f32_e32 v15, v15
	v_mul_f32_e32 v4, v4, v6
	v_mul_f32_e32 v4, v8, v4
	v_add_f32_e32 v6, 1.0, v15
	s_waitcnt lgkmcnt(6)
	v_lshlrev_b32_e32 v8, 16, v12
	v_rcp_f32_e32 v6, v6
	v_mul_f32_e32 v12, 0xbfb8aa3b, v8
	v_exp_f32_e32 v12, v12
	v_cvt_pk_bf16_f32 v4, v4, s0
	ds_write_b16 v5, v4 offset:16384
	v_mul_f32_e32 v4, v6, v7
	s_waitcnt lgkmcnt(6)
	v_lshlrev_b32_e32 v7, 16, v13
	v_mul_f32_e32 v4, v9, v4
	v_add_f32_e32 v6, 1.0, v12
	v_mul_f32_e32 v9, 0xbfb8aa3b, v7
	v_rcp_f32_e32 v6, v6
	v_exp_f32_e32 v9, v9
	v_cvt_pk_bf16_f32 v4, v4, s0
	ds_write_b16 v5, v4 offset:16896
	v_mul_f32_e32 v4, v6, v8
	v_add_f32_e32 v6, 1.0, v9
	v_rcp_f32_e32 v6, v6
	v_mul_f32_e32 v4, v10, v4
	v_cvt_pk_bf16_f32 v4, v4, s0
	ds_write_b16 v5, v4 offset:17408
	v_mul_f32_e32 v4, v6, v7
	s_waitcnt lgkmcnt(7)
	v_lshlrev_b32_e32 v6, 16, v14
	v_mul_f32_e32 v7, 0xbfb8aa3b, v6
	v_exp_f32_e32 v7, v7
	v_mul_f32_e32 v4, v11, v4
	v_cvt_pk_bf16_f32 v4, v4, s0
	ds_write_b16 v5, v4 offset:17920
	v_add_f32_e32 v4, 1.0, v7
	s_waitcnt lgkmcnt(7)
	v_lshlrev_b32_e32 v7, 16, v16
	v_rcp_f32_e32 v4, v4
	v_mul_f32_e32 v8, 0xbfb8aa3b, v7
	v_exp_f32_e32 v8, v8
	v_mul_f32_e32 v4, v4, v6
	v_mul_f32_e32 v0, v0, v4
	v_add_f32_e32 v4, 1.0, v8
	s_waitcnt lgkmcnt(6)
	v_lshlrev_b32_e32 v6, 16, v17
	v_rcp_f32_e32 v4, v4
	v_mul_f32_e32 v8, 0xbfb8aa3b, v6
	v_exp_f32_e32 v8, v8
	v_cvt_pk_bf16_f32 v0, v0, s0
	ds_write_b16 v5, v0 offset:24576
	v_mul_f32_e32 v0, v4, v7
	s_waitcnt lgkmcnt(6)
	v_lshlrev_b32_e32 v4, 16, v18
	v_mul_f32_e32 v0, v1, v0
	v_add_f32_e32 v1, 1.0, v8
	v_mul_f32_e32 v7, 0xbfb8aa3b, v4
	v_rcp_f32_e32 v1, v1
	v_exp_f32_e32 v7, v7
	v_cvt_pk_bf16_f32 v0, v0, s0
	ds_write_b16 v5, v0 offset:25088
	v_mul_f32_e32 v0, v1, v6
	v_add_f32_e32 v1, 1.0, v7
	v_rcp_f32_e32 v1, v1
	v_mul_f32_e32 v0, v2, v0
	v_cvt_pk_bf16_f32 v0, v0, s0
	ds_write_b16 v5, v0 offset:25600
	v_mul_f32_e32 v0, v1, v4
	v_mul_f32_e32 v0, v3, v0
	v_cvt_pk_bf16_f32 v0, v0, s0
	ds_write_b16 v5, v0 offset:26112
	v_ashrrev_i32_e32 v0, 31, v156
	v_lshrrev_b32_e32 v0, 27, v0
	v_add_u32_e32 v0, v156, v0
	v_ashrrev_i32_e32 v8, 5, v0
	v_and_b32_e32 v0, 0xffffffe0, v0
	v_sub_u32_e32 v2, v156, v0
	v_lshlrev_b32_e32 v0, 3, v2
	v_add_u32_e32 v6, s65, v8
	v_ashrrev_i32_e32 v1, 31, v0
	v_ashrrev_i32_e32 v7, 31, v6
	v_lshl_add_u64 v[4:5], v[0:1], 1, s[26:27]
	v_lshl_add_u32 v9, v2, 4, s23
	v_lshlrev_b64 v[6:7], 11, v[6:7]
	v_lshl_add_u32 v0, v8, 9, v9
	v_lshl_add_u64 v[6:7], v[4:5], 0, v[6:7]
	s_waitcnt lgkmcnt(0)
	s_barrier
	ds_read_b128 v[28:31], v0
	ds_read_b128 v[16:19], v0 offset:8192
	ds_read_b128 v[20:23], v0 offset:16384
	ds_read_b128 v[24:27], v0 offset:24576
	s_waitcnt lgkmcnt(3)
	global_store_dwordx4 v[6:7], v[28:31], off sc1
	s_nop 1
	v_add_u32_e32 v6, 16, v8
	v_lshl_add_u32 v0, v6, 9, v9
	v_add_u32_e32 v6, s65, v6
	v_ashrrev_i32_e32 v7, 31, v6
	v_lshlrev_b64 v[6:7], 11, v[6:7]
	v_lshl_add_u64 v[6:7], v[4:5], 0, v[6:7]
	s_waitcnt lgkmcnt(2)
	global_store_dwordx4 v[6:7], v[16:19], off sc1
	s_nop 1
	v_add_u32_e32 v6, 32, v8
	v_lshl_add_u32 v0, v6, 9, v9
	v_add_u32_e32 v6, s65, v6
	v_ashrrev_i32_e32 v7, 31, v6
	v_lshlrev_b64 v[6:7], 11, v[6:7]
	v_lshl_add_u64 v[6:7], v[4:5], 0, v[6:7]
	s_waitcnt lgkmcnt(1)
	global_store_dwordx4 v[6:7], v[20:23], off sc1
	s_nop 1
	v_add_u32_e32 v6, 48, v8
	v_lshl_add_u32 v0, v6, 9, v9
	v_add_u32_e32 v6, s65, v6
	v_ashrrev_i32_e32 v7, 31, v6
	v_lshlrev_b64 v[6:7], 11, v[6:7]
	v_lshl_add_u64 v[4:5], v[4:5], 0, v[6:7]
	s_waitcnt lgkmcnt(0)
	global_store_dwordx4 v[4:5], v[24:27], off sc1
	s_nop 1
	s_mov_b64 s[26:27], 0
	s_barrier

.LBB0_613:
	s_or_b64 exec, exec, s[26:27]
	v_bfe_u32 v32, v50, 3, 2
	v_ashrrev_i32_e32 v29, 3, v50
	v_lshlrev_b32_e64 v25, v32, 1
	v_and_b32_e32 v31, -4, v29
	v_and_b32_e32 v24, 31, v50
	v_sub_u32_e32 v8, v31, v25
	v_lshlrev_b32_e32 v8, 9, v8
	v_lshlrev_b32_e32 v28, 4, v24
	v_readlane_b32 s23, v254, 38
	v_cmp_lt_u32_e32 vcc, 7, v24
	s_nop 0
	v_add3_u32 v12, v8, s23, v28
	ds_read_b128 v[8:11], v12 offset:4096
	ds_read_b128 v[34:37], v12 offset:4608
	v_add_u32_e32 v30, 0x1000, v12
	v_cmp_lt_u32_e64 s[66:67], 7, v24
	v_cmp_lt_u32_e64 s[68:69], 15, v24
	v_cmp_eq_u32_e64 s[70:71], 3, v32
	s_mov_b64 s[72:73], exec
	s_movk_i32 s74, 0x200
	s_movk_i32 s75, 0x400
	v_lshl_add_u32 v96, s74, v32, v30
	v_lshl_add_u32 v97, s75, v32, v30
	v_or_b32_e32 v138, s43, v49
	v_or_b32_e32 v138, s42, v138
	v_lshlrev_b32_e32 v138, 1, v138
	v_mul_u32_u24_e32 v139, 0x840, v48
	v_add_u32_e32 v138, v138, v139
	s_mov_b64 exec, s[66:67]
	ds_read_b128 v[154:157], v30 offset:1024
	ds_read_b128 v[158:161], v30 offset:1536
	s_mov_b64 exec, s[68:69]
	ds_read_b128 v[162:165], v30 offset:2048
	ds_read_b128 v[166:169], v30 offset:2560
	ds_read_b128 v[170:173], v30 offset:3072
	ds_read_b128 v[174:177], v30 offset:3584
	s_mov_b64 exec, s[70:71]
	ds_read_b128 v[178:181], v30 offset:4096
	ds_read_b128 v[182:185], v30 offset:4608
	ds_read_b128 v[186:189], v30 offset:5120
	ds_read_b128 v[190:193], v30 offset:5632
	ds_read_b128 v[194:197], v30 offset:6144
	ds_read_b128 v[198:201], v30 offset:6656
	ds_read_b128 v[202:205], v30 offset:7168
	s_mov_b64 exec, s[72:73]
	s_waitcnt lgkmcnt(14)
	v_lshlrev_b32_e32 v12, 16, v8
	v_and_b32_e32 v13, 0xffff0000, v8
	v_lshlrev_b32_e32 v14, 16, v10
	v_and_b32_e32 v15, 0xffff0000, v10
	v_lshlrev_b32_e32 v10, 16, v11
	v_and_b32_e32 v11, 0xffff0000, v11
	v_pk_add_f32 v[12:13], v[12:13], 0 op_sel_hi:[1,0]
	v_lshlrev_b32_e32 v8, 16, v9
	v_and_b32_e32 v9, 0xffff0000, v9
	v_pk_add_f32 v[38:39], v[10:11], 0 op_sel_hi:[1,0]
	s_waitcnt lgkmcnt(13)
	v_lshlrev_b32_e32 v10, 16, v34
	v_and_b32_e32 v11, 0xffff0000, v34
	v_pk_add_f32 v[8:9], v[8:9], 0 op_sel_hi:[1,0]
	v_pk_add_f32 v[26:27], v[14:15], 0 op_sel_hi:[1,0]
	v_pk_add_f32 v[14:15], v[12:13], v[10:11]
	v_lshlrev_b32_e32 v10, 16, v35
	v_and_b32_e32 v11, 0xffff0000, v35
	v_pk_add_f32 v[12:13], v[8:9], v[10:11]
	v_lshlrev_b32_e32 v8, 16, v36
	v_and_b32_e32 v9, 0xffff0000, v36
	v_pk_add_f32 v[10:11], v[26:27], v[8:9]
	v_lshlrev_b32_e32 v8, 16, v37
	v_and_b32_e32 v9, 0xffff0000, v37
	v_pk_add_f32 v[8:9], v[38:39], v[8:9]
	s_mov_b64 exec, s[70:71]
	ds_read_b128 v[206:209], v30 offset:7680
	s_mov_b64 exec, s[72:73]
	ds_read_b128 v[98:101], v96
	s_mov_b64 exec, s[66:67]
	s_waitcnt lgkmcnt(14)
	v_lshlrev_b32_e32 v26, 16, v154
	v_and_b32_e32 v27, 0xffff0000, v154
	v_pk_add_f32 v[14:15], v[14:15], v[26:27]
	v_lshlrev_b32_e32 v26, 16, v155
	v_and_b32_e32 v27, 0xffff0000, v155
	v_pk_add_f32 v[12:13], v[12:13], v[26:27]
	v_lshlrev_b32_e32 v26, 16, v156
	v_and_b32_e32 v27, 0xffff0000, v156
	v_pk_add_f32 v[10:11], v[10:11], v[26:27]
	v_lshlrev_b32_e32 v26, 16, v157
	v_and_b32_e32 v27, 0xffff0000, v157
	v_pk_add_f32 v[8:9], v[8:9], v[26:27]
	s_waitcnt lgkmcnt(13)
	v_lshlrev_b32_e32 v26, 16, v158
	v_and_b32_e32 v27, 0xffff0000, v158
	v_pk_add_f32 v[14:15], v[14:15], v[26:27]
	v_lshlrev_b32_e32 v26, 16, v159
	v_and_b32_e32 v27, 0xffff0000, v159
	v_pk_add_f32 v[12:13], v[12:13], v[26:27]
	v_lshlrev_b32_e32 v26, 16, v160
	v_and_b32_e32 v27, 0xffff0000, v160
	v_pk_add_f32 v[10:11], v[10:11], v[26:27]
	v_lshlrev_b32_e32 v26, 16, v161
	v_and_b32_e32 v27, 0xffff0000, v161
	v_pk_add_f32 v[8:9], v[8:9], v[26:27]
	s_mov_b64 exec, s[72:73]
	ds_read_u16 v64, v138 offset:33792
	ds_read_u16 v65, v138 offset:34320
	s_mov_b64 exec, s[68:69]
	s_waitcnt lgkmcnt(14)
	v_lshlrev_b32_e32 v26, 16, v162
	v_and_b32_e32 v27, 0xffff0000, v162
	v_pk_add_f32 v[14:15], v[14:15], v[26:27]
	v_lshlrev_b32_e32 v26, 16, v163
	v_and_b32_e32 v27, 0xffff0000, v163
	v_pk_add_f32 v[12:13], v[12:13], v[26:27]
	v_lshlrev_b32_e32 v26, 16, v164
	v_and_b32_e32 v27, 0xffff0000, v164
	v_pk_add_f32 v[10:11], v[10:11], v[26:27]
	v_lshlrev_b32_e32 v26, 16, v165
	v_and_b32_e32 v27, 0xffff0000, v165
	v_pk_add_f32 v[8:9], v[8:9], v[26:27]
	s_waitcnt lgkmcnt(13)
	v_lshlrev_b32_e32 v26, 16, v166
	v_and_b32_e32 v27, 0xffff0000, v166
	v_pk_add_f32 v[14:15], v[14:15], v[26:27]
	v_lshlrev_b32_e32 v26, 16, v167
	v_and_b32_e32 v27, 0xffff0000, v167
	v_pk_add_f32 v[12:13], v[12:13], v[26:27]
	v_lshlrev_b32_e32 v26, 16, v168
	v_and_b32_e32 v27, 0xffff0000, v168
	v_pk_add_f32 v[10:11], v[10:11], v[26:27]
	v_lshlrev_b32_e32 v26, 16, v169
	v_and_b32_e32 v27, 0xffff0000, v169
	v_pk_add_f32 v[8:9], v[8:9], v[26:27]
	s_waitcnt lgkmcnt(12)
	v_lshlrev_b32_e32 v26, 16, v170
	v_and_b32_e32 v27, 0xffff0000, v170
	v_pk_add_f32 v[14:15], v[14:15], v[26:27]
	v_lshlrev_b32_e32 v26, 16, v171
	v_and_b32_e32 v27, 0xffff0000, v171
	v_pk_add_f32 v[12:13], v[12:13], v[26:27]
	v_lshlrev_b32_e32 v26, 16, v172
	v_and_b32_e32 v27, 0xffff0000, v172
	v_pk_add_f32 v[10:11], v[10:11], v[26:27]
	v_lshlrev_b32_e32 v26, 16, v173
	v_and_b32_e32 v27, 0xffff0000, v173
	v_pk_add_f32 v[8:9], v[8:9], v[26:27]
	s_waitcnt lgkmcnt(11)
	v_lshlrev_b32_e32 v26, 16, v174
	v_and_b32_e32 v27, 0xffff0000, v174
	v_pk_add_f32 v[14:15], v[14:15], v[26:27]
	v_lshlrev_b32_e32 v26, 16, v175
	v_and_b32_e32 v27, 0xffff0000, v175
	v_pk_add_f32 v[12:13], v[12:13], v[26:27]
	v_lshlrev_b32_e32 v26, 16, v176
	v_and_b32_e32 v27, 0xffff0000, v176
	v_pk_add_f32 v[10:11], v[10:11], v[26:27]
	v_lshlrev_b32_e32 v26, 16, v177
	v_and_b32_e32 v27, 0xffff0000, v177
	v_pk_add_f32 v[8:9], v[8:9], v[26:27]
	s_mov_b64 exec, s[72:73]
	ds_read_u16 v66, v138 offset:34848
	ds_read_b128 v[102:105], v30
	ds_read_u16 v67, v138 offset:42240
	ds_read_u16 v68, v138 offset:35376
	s_mov_b64 exec, s[70:71]
	s_waitcnt lgkmcnt(14)
	v_lshlrev_b32_e32 v26, 16, v178
	v_and_b32_e32 v27, 0xffff0000, v178
	v_pk_add_f32 v[14:15], v[14:15], v[26:27]
	v_lshlrev_b32_e32 v26, 16, v179
	v_and_b32_e32 v27, 0xffff0000, v179
	v_pk_add_f32 v[12:13], v[12:13], v[26:27]
	v_lshlrev_b32_e32 v26, 16, v180
	v_and_b32_e32 v27, 0xffff0000, v180
	v_pk_add_f32 v[10:11], v[10:11], v[26:27]
	v_lshlrev_b32_e32 v26, 16, v181
	v_and_b32_e32 v27, 0xffff0000, v181
	v_pk_add_f32 v[8:9], v[8:9], v[26:27]
	s_waitcnt lgkmcnt(13)
	v_lshlrev_b32_e32 v26, 16, v182
	v_and_b32_e32 v27, 0xffff0000, v182
	v_pk_add_f32 v[14:15], v[14:15], v[26:27]
	v_lshlrev_b32_e32 v26, 16, v183
	v_and_b32_e32 v27, 0xffff0000, v183
	v_pk_add_f32 v[12:13], v[12:13], v[26:27]
	v_lshlrev_b32_e32 v26, 16, v184
	v_and_b32_e32 v27, 0xffff0000, v184
	v_pk_add_f32 v[10:11], v[10:11], v[26:27]
	v_lshlrev_b32_e32 v26, 16, v185
	v_and_b32_e32 v27, 0xffff0000, v185
	v_pk_add_f32 v[8:9], v[8:9], v[26:27]
	s_waitcnt lgkmcnt(12)
	v_lshlrev_b32_e32 v26, 16, v186
	v_and_b32_e32 v27, 0xffff0000, v186
	v_pk_add_f32 v[14:15], v[14:15], v[26:27]
	v_lshlrev_b32_e32 v26, 16, v187
	v_and_b32_e32 v27, 0xffff0000, v187
	v_pk_add_f32 v[12:13], v[12:13], v[26:27]
	v_lshlrev_b32_e32 v26, 16, v188
	v_and_b32_e32 v27, 0xffff0000, v188
	v_pk_add_f32 v[10:11], v[10:11], v[26:27]
	v_lshlrev_b32_e32 v26, 16, v189
	v_and_b32_e32 v27, 0xffff0000, v189
	v_pk_add_f32 v[8:9], v[8:9], v[26:27]
	s_waitcnt lgkmcnt(11)
	v_lshlrev_b32_e32 v26, 16, v190
	v_and_b32_e32 v27, 0xffff0000, v190
	v_pk_add_f32 v[14:15], v[14:15], v[26:27]
	v_lshlrev_b32_e32 v26, 16, v191
	v_and_b32_e32 v27, 0xffff0000, v191
	v_pk_add_f32 v[12:13], v[12:13], v[26:27]
	v_lshlrev_b32_e32 v26, 16, v192
	v_and_b32_e32 v27, 0xffff0000, v192
	v_pk_add_f32 v[10:11], v[10:11], v[26:27]
	v_lshlrev_b32_e32 v26, 16, v193
	v_and_b32_e32 v27, 0xffff0000, v193
	v_pk_add_f32 v[8:9], v[8:9], v[26:27]
	s_waitcnt lgkmcnt(10)
	v_lshlrev_b32_e32 v26, 16, v194
	v_and_b32_e32 v27, 0xffff0000, v194
	v_pk_add_f32 v[14:15], v[14:15], v[26:27]
	v_lshlrev_b32_e32 v26, 16, v195
	v_and_b32_e32 v27, 0xffff0000, v195
	v_pk_add_f32 v[12:13], v[12:13], v[26:27]
	v_lshlrev_b32_e32 v26, 16, v196
	v_and_b32_e32 v27, 0xffff0000, v196
	v_pk_add_f32 v[10:11], v[10:11], v[26:27]
	v_lshlrev_b32_e32 v26, 16, v197
	v_and_b32_e32 v27, 0xffff0000, v197
	v_pk_add_f32 v[8:9], v[8:9], v[26:27]
	s_waitcnt lgkmcnt(9)
	v_lshlrev_b32_e32 v26, 16, v198
	v_and_b32_e32 v27, 0xffff0000, v198
	v_pk_add_f32 v[14:15], v[14:15], v[26:27]
	v_lshlrev_b32_e32 v26, 16, v199
	v_and_b32_e32 v27, 0xffff0000, v199
	v_pk_add_f32 v[12:13], v[12:13], v[26:27]
	v_lshlrev_b32_e32 v26, 16, v200
	v_and_b32_e32 v27, 0xffff0000, v200
	v_pk_add_f32 v[10:11], v[10:11], v[26:27]
	v_lshlrev_b32_e32 v26, 16, v201
	v_and_b32_e32 v27, 0xffff0000, v201
	v_pk_add_f32 v[8:9], v[8:9], v[26:27]
	s_waitcnt lgkmcnt(8)
	v_lshlrev_b32_e32 v26, 16, v202
	v_and_b32_e32 v27, 0xffff0000, v202
	v_pk_add_f32 v[14:15], v[14:15], v[26:27]
	v_lshlrev_b32_e32 v26, 16, v203
	v_and_b32_e32 v27, 0xffff0000, v203
	v_pk_add_f32 v[12:13], v[12:13], v[26:27]
	v_lshlrev_b32_e32 v26, 16, v204
	v_and_b32_e32 v27, 0xffff0000, v204
	v_pk_add_f32 v[10:11], v[10:11], v[26:27]
	v_lshlrev_b32_e32 v26, 16, v205
	v_and_b32_e32 v27, 0xffff0000, v205
	v_pk_add_f32 v[8:9], v[8:9], v[26:27]
	s_waitcnt lgkmcnt(7)
	v_lshlrev_b32_e32 v26, 16, v206
	v_and_b32_e32 v27, 0xffff0000, v206
	v_pk_add_f32 v[14:15], v[14:15], v[26:27]
	v_lshlrev_b32_e32 v26, 16, v207
	v_and_b32_e32 v27, 0xffff0000, v207
	v_pk_add_f32 v[12:13], v[12:13], v[26:27]
	v_lshlrev_b32_e32 v26, 16, v208
	v_and_b32_e32 v27, 0xffff0000, v208
	v_pk_add_f32 v[10:11], v[10:11], v[26:27]
	v_lshlrev_b32_e32 v26, 16, v209
	v_and_b32_e32 v27, 0xffff0000, v209
	v_pk_add_f32 v[8:9], v[8:9], v[26:27]
	s_mov_b64 exec, s[72:73]
	ds_read_u16 v69, v138 offset:42768
	ds_read_b128 v[106:109], v97
	ds_read_u16 v70, v138 offset:43296
	ds_read_u16 v71, v138 offset:50688
	ds_read_u16 v72, v138 offset:43824
	ds_read_b128 v[110:113], v96 offset:512
	ds_read_u16 v73, v138 offset:59136
	ds_read_u16 v74, v138 offset:33824
	v_add_u32_e32 v26, s47, v31
	v_sub_u32_e32 v27, v26, v25
	v_add_u32_e32 v26, v26, v25
	v_max_i32_e32 v27, 0, v27
	v_min_i32_e32 v26, s46, v26
	v_sub_u32_e32 v26, v26, v27
	v_cvt_f32_i32_e32 v26, v26
	v_lshlrev_b32_e32 v33, 9, v31
	v_readlane_b32 s49, v254, 38
	v_add_u32_e32 v24, 0, v28
	v_div_scale_f32 v27, s[26:27], v26, v26, 1.0
	v_add3_u32 v33, s49, v33, v28
	s_waitcnt lgkmcnt(14)
	v_mov_b32_e32 v34, v98
	v_mov_b32_e32 v35, v99
	v_mov_b32_e32 v36, v100
	v_mov_b32_e32 v37, v101
	v_rcp_f32_e32 v33, v27
	s_movk_i32 s48, 0x210
	s_movk_i32 s23, 0x400
	v_lshl_add_u32 v45, s23, v32, v30
	v_fma_f32 v38, -v27, v33, 1.0
	v_fmac_f32_e32 v33, v38, v33
	v_div_scale_f32 v38, vcc, 1.0, v26, 1.0
	v_mul_f32_e32 v39, v38, v33
	v_fma_f32 v40, -v27, v39, v38
	v_fmac_f32_e32 v39, v40, v33
	v_fma_f32 v27, -v27, v39, v38
	v_div_fmas_f32 v27, v27, v33, v39
	v_div_fixup_f32 v26, v27, v26, 1.0
	v_lshlrev_b32_e32 v38, 16, v34
	v_and_b32_e32 v39, 0xffff0000, v34
	v_pk_fma_f32 v[38:39], v[26:27], v[14:15], v[38:39] op_sel_hi:[0,1,1] neg_lo:[0,0,1] neg_hi:[0,0,1]
	v_cvt_pk_bf16_f32 v34, v38, v39
	v_lshlrev_b32_e32 v38, 16, v35
	v_and_b32_e32 v39, 0xffff0000, v35
	v_pk_fma_f32 v[38:39], v[26:27], v[12:13], v[38:39] op_sel_hi:[0,1,1] neg_lo:[0,0,1] neg_hi:[0,0,1]
	v_cvt_pk_bf16_f32 v35, v38, v39
	v_lshlrev_b32_e32 v38, 16, v36
	v_and_b32_e32 v39, 0xffff0000, v36
	v_pk_fma_f32 v[38:39], v[26:27], v[10:11], v[38:39] op_sel_hi:[0,1,1] neg_lo:[0,0,1] neg_hi:[0,0,1]
	v_cvt_pk_bf16_f32 v36, v38, v39
	v_lshlrev_b32_e32 v38, 16, v37
	v_and_b32_e32 v39, 0xffff0000, v37
	v_pk_fma_f32 v[26:27], v[26:27], v[8:9], v[38:39] op_sel_hi:[0,1,1] neg_lo:[0,0,1] neg_hi:[0,0,1]
	v_cvt_pk_bf16_f32 v37, v26, v27
	v_mad_u64_u32 v[26:27], s[26:27], v31, s48, v[24:25]
	ds_write_b128 v26, v[34:37]
	s_waitcnt lgkmcnt(11)
	v_mov_b32_e32 v34, v102
	v_mov_b32_e32 v35, v103
	v_mov_b32_e32 v36, v104
	v_mov_b32_e32 v37, v105
	ds_read_u16 v75, v138 offset:59664
	ds_read_b128 v[114:117], v30 offset:512
	ds_read_u16 v76, v138 offset:51216
	s_waitcnt lgkmcnt(10)
	v_mov_b32_e32 v38, v106
	v_mov_b32_e32 v39, v107
	v_mov_b32_e32 v40, v108
	v_mov_b32_e32 v41, v109
	ds_read_u16 v77, v138 offset:60192
	ds_read_u16 v78, v138 offset:60720
	ds_read_b128 v[118:121], v97 offset:512
	ds_read_u16 v79, v138 offset:34352
	v_or_b32_e32 v27, 1, v31
	v_add_u32_e32 v44, s47, v27
	v_or_b32_e32 v29, 3, v29
	v_lshlrev_b32_e32 v42, 16, v34
	v_lshlrev_b32_e32 v32, 16, v38
	v_and_b32_e32 v33, 0xffff0000, v38
	v_and_b32_e32 v43, 0xffff0000, v34
	v_pk_add_f32 v[32:33], v[32:33], v[42:43] neg_lo:[0,1] neg_hi:[0,1]
	v_lshlrev_b32_e32 v34, 16, v35
	v_pk_add_f32 v[32:33], v[14:15], v[32:33]
	v_lshlrev_b32_e32 v14, 16, v39
	v_and_b32_e32 v15, 0xffff0000, v39
	v_and_b32_e32 v35, 0xffff0000, v35
	v_pk_add_f32 v[14:15], v[14:15], v[34:35] neg_lo:[0,1] neg_hi:[0,1]
	s_and_b32 s23, s45, 0xffffff80
	v_pk_add_f32 v[34:35], v[12:13], v[14:15]
	v_lshlrev_b32_e32 v12, 16, v40
	v_and_b32_e32 v13, 0xffff0000, v40
	v_lshlrev_b32_e32 v14, 16, v36
	v_and_b32_e32 v15, 0xffff0000, v36
	v_pk_add_f32 v[12:13], v[12:13], v[14:15] neg_lo:[0,1] neg_hi:[0,1]
	v_mul_u32_u24_e32 v56, 0x840, v48
	v_pk_add_f32 v[38:39], v[10:11], v[12:13]
	v_lshlrev_b32_e32 v10, 16, v41
	v_and_b32_e32 v11, 0xffff0000, v41
	v_lshlrev_b32_e32 v12, 16, v37
	v_and_b32_e32 v13, 0xffff0000, v37
	v_pk_add_f32 v[10:11], v[10:11], v[12:13] neg_lo:[0,1] neg_hi:[0,1]
	s_add_i32 s23, s23, 0
	v_pk_add_f32 v[36:37], v[8:9], v[10:11]
	v_sub_u32_e32 v8, v44, v25
	v_max_i32_e32 v12, 0, v8
	v_add_u32_e32 v8, v44, v25
	v_min_i32_e32 v13, s46, v8
	v_sub_u32_e32 v12, v13, v12
	v_cvt_f32_i32_e32 v12, v12
	v_lshlrev_b32_e32 v8, 9, v27
	v_add3_u32 v8, s49, v8, v28
	s_waitcnt lgkmcnt(10)
	v_mov_b32_e32 v8, v110
	v_mov_b32_e32 v9, v111
	v_mov_b32_e32 v10, v112
	v_mov_b32_e32 v11, v113
	ds_read_u16 v80, v138 offset:34880
	ds_read_u16 v81, v138 offset:42272
	ds_read_b128 v[122:125], v96 offset:1024
	ds_read_u16 v82, v138 offset:51744
	v_div_scale_f32 v13, s[26:27], v12, v12, 1.0
	v_rcp_f32_e32 v14, v13
	s_nop 0
	v_fma_f32 v15, -v13, v14, 1.0
	v_fmac_f32_e32 v14, v15, v14
	v_div_scale_f32 v15, vcc, 1.0, v12, 1.0
	v_mul_f32_e32 v27, v15, v14
	v_fma_f32 v40, -v13, v27, v15
	v_fmac_f32_e32 v27, v40, v14
	v_fma_f32 v13, -v13, v27, v15
	v_div_fmas_f32 v13, v13, v14, v27
	v_div_fixup_f32 v12, v13, v12, 1.0
	v_lshlrev_b32_e32 v14, 16, v8
	v_and_b32_e32 v15, 0xffff0000, v8
	v_pk_fma_f32 v[14:15], v[12:13], v[32:33], v[14:15] op_sel_hi:[0,1,1] neg_lo:[0,0,1] neg_hi:[0,0,1]
	v_cvt_pk_bf16_f32 v8, v14, v15
	v_lshlrev_b32_e32 v14, 16, v9
	v_and_b32_e32 v15, 0xffff0000, v9
	v_pk_fma_f32 v[14:15], v[12:13], v[34:35], v[14:15] op_sel_hi:[0,1,1] neg_lo:[0,0,1] neg_hi:[0,0,1]
	v_cvt_pk_bf16_f32 v9, v14, v15
	v_lshlrev_b32_e32 v14, 16, v10
	v_and_b32_e32 v15, 0xffff0000, v10
	v_pk_fma_f32 v[14:15], v[12:13], v[38:39], v[14:15] op_sel_hi:[0,1,1] neg_lo:[0,0,1] neg_hi:[0,0,1]
	v_cvt_pk_bf16_f32 v10, v14, v15
	v_lshlrev_b32_e32 v14, 16, v11
	v_and_b32_e32 v15, 0xffff0000, v11
	v_pk_fma_f32 v[12:13], v[12:13], v[36:37], v[14:15] op_sel_hi:[0,1,1] neg_lo:[0,0,1] neg_hi:[0,0,1]
	v_cvt_pk_bf16_f32 v11, v12, v13
	ds_write_b128 v26, v[8:11] offset:528
	s_waitcnt lgkmcnt(10)
	v_mov_b32_e32 v8, v114
	v_mov_b32_e32 v9, v115
	v_mov_b32_e32 v10, v116
	v_mov_b32_e32 v11, v117
	ds_read_u16 v83, v138 offset:35408
	ds_read_u16 v84, v138 offset:52272
	ds_read_b128 v[126:129], v97 offset:1024
	ds_read_u16 v85, v138 offset:42800
	s_waitcnt lgkmcnt(10)
	v_mov_b32_e32 v12, v118
	v_mov_b32_e32 v13, v119
	v_mov_b32_e32 v14, v120
	v_mov_b32_e32 v15, v121
	ds_read_u16 v86, v138 offset:43328
	ds_read_u16 v87, v138 offset:50720
	ds_read_b128 v[130:133], v30 offset:1024
	ds_read_u16 v88, v138 offset:43856
	v_or_b32_e32 v27, 2, v31
	v_add_u32_e32 v31, s47, v27
	v_lshlrev_b32_e32 v42, 16, v8
	v_lshlrev_b32_e32 v40, 16, v12
	v_and_b32_e32 v41, 0xffff0000, v12
	v_and_b32_e32 v43, 0xffff0000, v8
	v_lshlrev_b32_e32 v12, 16, v13
	v_and_b32_e32 v13, 0xffff0000, v13
	v_lshlrev_b32_e32 v8, 16, v9
	v_and_b32_e32 v9, 0xffff0000, v9
	v_pk_add_f32 v[8:9], v[12:13], v[8:9] neg_lo:[0,1] neg_hi:[0,1]
	v_lshlrev_b32_e32 v12, 16, v10
	v_pk_add_f32 v[34:35], v[34:35], v[8:9]
	v_lshlrev_b32_e32 v8, 16, v14
	v_and_b32_e32 v9, 0xffff0000, v14
	v_and_b32_e32 v13, 0xffff0000, v10
	v_pk_add_f32 v[8:9], v[8:9], v[12:13] neg_lo:[0,1] neg_hi:[0,1]
	v_lshlrev_b32_e32 v10, 16, v11
	v_pk_add_f32 v[38:39], v[38:39], v[8:9]
	v_lshlrev_b32_e32 v8, 16, v15
	v_and_b32_e32 v9, 0xffff0000, v15
	v_and_b32_e32 v11, 0xffff0000, v11
	v_pk_add_f32 v[8:9], v[8:9], v[10:11] neg_lo:[0,1] neg_hi:[0,1]
	v_pk_add_f32 v[40:41], v[40:41], v[42:43] neg_lo:[0,1] neg_hi:[0,1]
	v_pk_add_f32 v[36:37], v[36:37], v[8:9]
	v_sub_u32_e32 v8, v31, v25
	v_max_i32_e32 v12, 0, v8
	v_add_u32_e32 v8, v31, v25
	v_min_i32_e32 v13, s46, v8
	v_sub_u32_e32 v12, v13, v12
	v_cvt_f32_i32_e32 v12, v12
	v_lshlrev_b32_e32 v8, 9, v27
	v_add3_u32 v8, s49, v8, v28
	s_waitcnt lgkmcnt(10)
	v_mov_b32_e32 v8, v122
	v_mov_b32_e32 v9, v123
	v_mov_b32_e32 v10, v124
	v_mov_b32_e32 v11, v125
	ds_read_u16 v89, v138 offset:51248
	ds_read_u16 v90, v138 offset:59168
	ds_read_b128 v[134:137], v96 offset:1536
	ds_read_u16 v91, v138 offset:51776
	v_div_scale_f32 v13, s[26:27], v12, v12, 1.0
	v_rcp_f32_e32 v14, v13
	v_pk_add_f32 v[32:33], v[32:33], v[40:41]
	v_fma_f32 v15, -v13, v14, 1.0
	v_fmac_f32_e32 v14, v15, v14
	v_div_scale_f32 v15, vcc, 1.0, v12, 1.0
	v_mul_f32_e32 v27, v15, v14
	v_fma_f32 v31, -v13, v27, v15
	v_fmac_f32_e32 v27, v31, v14
	v_fma_f32 v13, -v13, v27, v15
	v_div_fmas_f32 v13, v13, v14, v27
	v_div_fixup_f32 v12, v13, v12, 1.0
	v_lshlrev_b32_e32 v14, 16, v8
	v_and_b32_e32 v15, 0xffff0000, v8
	v_pk_fma_f32 v[14:15], v[12:13], v[32:33], v[14:15] op_sel_hi:[0,1,1] neg_lo:[0,0,1] neg_hi:[0,0,1]
	v_cvt_pk_bf16_f32 v8, v14, v15
	v_lshlrev_b32_e32 v14, 16, v9
	v_and_b32_e32 v15, 0xffff0000, v9
	v_pk_fma_f32 v[14:15], v[12:13], v[34:35], v[14:15] op_sel_hi:[0,1,1] neg_lo:[0,0,1] neg_hi:[0,0,1]
	v_cvt_pk_bf16_f32 v9, v14, v15
	v_lshlrev_b32_e32 v14, 16, v10
	v_and_b32_e32 v15, 0xffff0000, v10
	v_pk_fma_f32 v[14:15], v[12:13], v[38:39], v[14:15] op_sel_hi:[0,1,1] neg_lo:[0,0,1] neg_hi:[0,0,1]
	v_cvt_pk_bf16_f32 v10, v14, v15
	v_lshlrev_b32_e32 v14, 16, v11
	v_and_b32_e32 v15, 0xffff0000, v11
	v_pk_fma_f32 v[12:13], v[12:13], v[36:37], v[14:15] op_sel_hi:[0,1,1] neg_lo:[0,0,1] neg_hi:[0,0,1]
	v_cvt_pk_bf16_f32 v11, v12, v13
	ds_write_b128 v26, v[8:11] offset:1056
	s_waitcnt lgkmcnt(10)
	v_mov_b32_e32 v8, v126
	v_mov_b32_e32 v9, v127
	v_mov_b32_e32 v10, v128
	v_mov_b32_e32 v11, v129
	ds_read_u16 v92, v138 offset:59696
	ds_read_u16 v93, v138 offset:52304
	ds_read_u16 v94, v138 offset:60224
	ds_read_u16 v95, v138 offset:60752
	s_waitcnt lgkmcnt(10)
	v_mov_b32_e32 v12, v130
	v_mov_b32_e32 v13, v131
	v_mov_b32_e32 v14, v132
	v_mov_b32_e32 v15, v133
	v_lshlrev_b32_e32 v26, 16, v11
	v_and_b32_e32 v27, 0xffff0000, v11
	v_lshlrev_b32_e32 v30, 16, v15
	v_and_b32_e32 v31, 0xffff0000, v15
	v_pk_add_f32 v[26:27], v[26:27], v[30:31] neg_lo:[0,1] neg_hi:[0,1]
	v_lshlrev_b32_e32 v30, 16, v10
	v_and_b32_e32 v31, 0xffff0000, v10
	v_lshlrev_b32_e32 v10, 16, v14
	v_and_b32_e32 v11, 0xffff0000, v14
	v_pk_add_f32 v[10:11], v[30:31], v[10:11] neg_lo:[0,1] neg_hi:[0,1]
	v_lshlrev_b32_e32 v30, 16, v13
	v_pk_add_f32 v[14:15], v[38:39], v[10:11]
	v_lshlrev_b32_e32 v10, 16, v9
	v_and_b32_e32 v11, 0xffff0000, v9
	v_and_b32_e32 v31, 0xffff0000, v13
	v_pk_add_f32 v[10:11], v[10:11], v[30:31] neg_lo:[0,1] neg_hi:[0,1]
	v_and_b32_e32 v9, 0xffff0000, v12
	v_pk_add_f32 v[30:31], v[34:35], v[10:11]
	v_lshlrev_b32_e32 v10, 16, v8
	v_and_b32_e32 v11, 0xffff0000, v8
	v_lshlrev_b32_e32 v8, 16, v12
	v_pk_add_f32 v[8:9], v[10:11], v[8:9] neg_lo:[0,1] neg_hi:[0,1]
	v_pk_add_f32 v[26:27], v[36:37], v[26:27]
	v_pk_add_f32 v[12:13], v[32:33], v[8:9]
	v_add_u32_e32 v8, s47, v29
	v_sub_u32_e32 v9, v8, v25
	v_add_u32_e32 v8, v8, v25
	v_max_i32_e32 v32, 0, v9
	v_min_i32_e32 v25, s46, v8
	v_sub_u32_e32 v25, v25, v32
	v_cvt_f32_i32_e32 v25, v25
	v_lshlrev_b32_e32 v8, 9, v29
	v_add3_u32 v8, s49, v8, v28
	s_waitcnt lgkmcnt(6)
	v_mov_b32_e32 v8, v134
	v_mov_b32_e32 v9, v135
	v_mov_b32_e32 v10, v136
	v_mov_b32_e32 v11, v137
	v_div_scale_f32 v28, s[26:27], v25, v25, 1.0
	v_rcp_f32_e32 v32, v28
	s_nop 0
	v_fma_f32 v33, -v28, v32, 1.0
	v_fmac_f32_e32 v32, v33, v32
	v_div_scale_f32 v33, vcc, 1.0, v25, 1.0
	v_mul_f32_e32 v34, v33, v32
	v_fma_f32 v35, -v28, v34, v33
	v_fmac_f32_e32 v34, v35, v32
	v_fma_f32 v28, -v28, v34, v33
	v_div_fmas_f32 v28, v28, v32, v34
	v_div_fixup_f32 v28, v28, v25, 1.0
	v_lshlrev_b32_e32 v32, 16, v8
	v_and_b32_e32 v33, 0xffff0000, v8
	v_pk_fma_f32 v[12:13], v[28:29], v[12:13], v[32:33] op_sel_hi:[0,1,1] neg_lo:[0,0,1] neg_hi:[0,0,1]
	v_cvt_pk_bf16_f32 v8, v12, v13
	v_lshlrev_b32_e32 v12, 16, v9
	v_and_b32_e32 v13, 0xffff0000, v9
	v_pk_fma_f32 v[12:13], v[28:29], v[30:31], v[12:13] op_sel_hi:[0,1,1] neg_lo:[0,0,1] neg_hi:[0,0,1]
	v_cvt_pk_bf16_f32 v9, v12, v13
	v_lshlrev_b32_e32 v12, 16, v10
	v_and_b32_e32 v13, 0xffff0000, v10
	v_pk_fma_f32 v[12:13], v[28:29], v[14:15], v[12:13] op_sel_hi:[0,1,1] neg_lo:[0,0,1] neg_hi:[0,0,1]
	v_cvt_pk_bf16_f32 v10, v12, v13
	v_lshlrev_b32_e32 v12, 16, v11
	v_and_b32_e32 v13, 0xffff0000, v11
	v_pk_fma_f32 v[12:13], v[28:29], v[26:27], v[12:13] op_sel_hi:[0,1,1] neg_lo:[0,0,1] neg_hi:[0,0,1]
	v_cvt_pk_bf16_f32 v11, v12, v13
	v_mad_u64_u32 v[12:13], s[26:27], v29, s48, v[24:25]
	ds_write_b128 v12, v[8:11]
	v_mul_u32_u24_e32 v8, 0x210, v49
	v_or_b32_e32 v49, s43, v49
	v_or_b32_e32 v51, s42, v49
	v_add_u32_e32 v48, s24, v51
	v_ashrrev_i32_e32 v49, 31, v48
	v_add3_u32 v12, s23, v148, v8
	v_lshl_add_u64 v[48:49], v[48:49], 2, s[88:89]
	s_waitcnt lgkmcnt(0)
	s_barrier
	ds_read_b128 v[40:43], v12
	ds_read_b128 v[44:47], v12 offset:64
	ds_read_b128 v[32:35], v12 offset:8448
	ds_read_b128 v[36:39], v12 offset:8512
	ds_read_b128 v[24:27], v12 offset:16896
	ds_read_b128 v[28:31], v12 offset:16960
	ds_read_b128 v[8:11], v12 offset:25344
	ds_read_b128 v[12:15], v12 offset:25408
	global_load_dword v57, v[48:49], off
	v_lshlrev_b32_e32 v51, 1, v51
	v_add3_u32 v51, 0, v51, v56
	s_waitcnt vmcnt(4) lgkmcnt(7)
	v_mfma_f32_16x16x32_bf16 v[52:55], v[40:43], v[16:19], 0
	v_readlane_b32 s26, v255, 11
	v_readlane_b32 s27, v255, 12
	s_waitcnt lgkmcnt(0)
	v_lshlrev_b32_e32 v56, 16, v64
	v_mul_f32_e32 v58, 0xbfb8aa3b, v56
	v_exp_f32_e32 v58, v58
	s_waitcnt vmcnt(3)
	v_mfma_f32_16x16x32_bf16 v[52:55], v[44:47], v[20:23], v[52:55]
	v_add_f32_e32 v58, 1.0, v58
	v_rcp_f32_e32 v58, v58
	s_nop 0
	v_mul_f32_e32 v56, v58, v56
	s_waitcnt vmcnt(0)
	s_nop 2
	v_mul_f32_e32 v52, v57, v52
	v_mul_f32_e32 v52, v52, v56
	v_cvt_pk_bf16_f32 v52, v52, s0
	ds_write_b16 v51, v52 offset:33792
	s_nop 0
	v_mul_f32_e32 v53, v57, v53
	v_lshlrev_b32_e32 v52, 16, v65
	v_mul_f32_e32 v56, 0xbfb8aa3b, v52
	v_exp_f32_e32 v56, v56
	s_nop 0
	v_add_f32_e32 v56, 1.0, v56
	v_rcp_f32_e32 v56, v56
	s_nop 0
	v_mul_f32_e32 v52, v56, v52
	v_mul_f32_e32 v52, v53, v52
	v_cvt_pk_bf16_f32 v52, v52, s0
	ds_write_b16 v51, v52 offset:34320
	v_mul_f32_e32 v53, v57, v54
	v_lshlrev_b32_e32 v52, 16, v66
	v_mul_f32_e32 v54, 0xbfb8aa3b, v52
	v_exp_f32_e32 v54, v54
	s_nop 0
	v_lshlrev_b32_e32 v56, 16, v67
	v_mul_f32_e32 v58, 0xbfb8aa3b, v56
	v_exp_f32_e32 v58, v58
	v_add_f32_e32 v54, 1.0, v54
	v_rcp_f32_e32 v54, v54
	v_add_f32_e32 v58, 1.0, v58
	v_rcp_f32_e32 v58, v58
	v_mul_f32_e32 v52, v54, v52
	v_mul_f32_e32 v52, v53, v52
	v_cvt_pk_bf16_f32 v52, v52, s0
	ds_write_b16 v51, v52 offset:34848
	v_mul_f32_e32 v53, v57, v55
	v_mul_f32_e32 v56, v58, v56
	v_lshlrev_b32_e32 v52, 16, v68
	v_mul_f32_e32 v54, 0xbfb8aa3b, v52
	v_exp_f32_e32 v54, v54
	s_nop 0
	v_add_f32_e32 v54, 1.0, v54
	v_rcp_f32_e32 v54, v54
	s_nop 0
	v_mul_f32_e32 v52, v54, v52
	v_mul_f32_e32 v52, v53, v52
	v_cvt_pk_bf16_f32 v52, v52, s0
	ds_write_b16 v51, v52 offset:35376
	v_mfma_f32_16x16x32_bf16 v[52:55], v[32:35], v[16:19], 0
	v_mfma_f32_16x16x32_bf16 v[52:55], v[36:39], v[20:23], v[52:55]
	s_nop 7
	v_mul_f32_e32 v52, v57, v52
	v_mul_f32_e32 v52, v52, v56
	v_cvt_pk_bf16_f32 v52, v52, s0
	ds_write_b16 v51, v52 offset:42240
	s_nop 0
	v_mul_f32_e32 v53, v57, v53
	s_nop 0
	v_lshlrev_b32_e32 v52, 16, v69
	v_mul_f32_e32 v56, 0xbfb8aa3b, v52
	v_exp_f32_e32 v56, v56
	s_nop 0
	v_add_f32_e32 v56, 1.0, v56
	v_rcp_f32_e32 v56, v56
	s_nop 0
	v_mul_f32_e32 v52, v56, v52
	v_mul_f32_e32 v52, v53, v52
	v_cvt_pk_bf16_f32 v52, v52, s0
	ds_write_b16 v51, v52 offset:42768
	v_mul_f32_e32 v53, v57, v54
	v_lshlrev_b32_e32 v52, 16, v70
	v_mul_f32_e32 v54, 0xbfb8aa3b, v52
	v_exp_f32_e32 v54, v54
	s_nop 0
	v_add_f32_e32 v54, 1.0, v54
	v_rcp_f32_e32 v54, v54
	s_nop 0
	v_mul_f32_e32 v52, v54, v52
	v_mul_f32_e32 v52, v53, v52
	v_cvt_pk_bf16_f32 v52, v52, s0
	ds_write_b16 v51, v52 offset:43296
	v_mul_f32_e32 v53, v57, v55
	v_lshlrev_b32_e32 v52, 16, v72
	v_mul_f32_e32 v54, 0xbfb8aa3b, v52
	v_exp_f32_e32 v54, v54
	s_nop 0
	v_add_f32_e32 v54, 1.0, v54
	v_rcp_f32_e32 v54, v54
	s_nop 0
	v_mul_f32_e32 v52, v54, v52
	v_mul_f32_e32 v52, v53, v52
	v_cvt_pk_bf16_f32 v52, v52, s0
	ds_write_b16 v51, v52 offset:43824
	v_mfma_f32_16x16x32_bf16 v[52:55], v[24:27], v[16:19], 0
	v_mfma_f32_16x16x32_bf16 v[16:19], v[8:11], v[16:19], 0
	v_mfma_f32_16x16x32_bf16 v[52:55], v[28:31], v[20:23], v[52:55]
	v_mfma_f32_16x16x32_bf16 v[16:19], v[12:15], v[20:23], v[16:19]
	s_nop 0
	s_nop 5
	v_mul_f32_e32 v52, v57, v52
	v_mul_f32_e32 v53, v57, v53
	s_nop 0
	v_lshlrev_b32_e32 v20, 16, v73
	v_mul_f32_e32 v21, 0xbfb8aa3b, v20
	v_exp_f32_e32 v21, v21
	v_mul_f32_e32 v16, v57, v16
	v_mul_f32_e32 v17, v57, v17
	v_add_f32_e32 v21, 1.0, v21
	v_rcp_f32_e32 v21, v21
	s_nop 0
	v_mul_f32_e32 v20, v21, v20
	v_lshlrev_b32_e32 v56, 16, v71
	v_mul_f32_e32 v58, 0xbfb8aa3b, v56
	v_exp_f32_e32 v58, v58
	v_mul_f32_e32 v16, v16, v20
	v_cvt_pk_bf16_f32 v16, v16, s0
	ds_write_b16 v51, v16 offset:59136
	v_add_f32_e32 v58, 1.0, v58
	v_rcp_f32_e32 v58, v58
	s_nop 0
	v_lshlrev_b32_e32 v21, 16, v74
	v_mul_f32_e32 v22, 0xbfb8aa3b, v21
	v_mul_f32_e32 v56, v58, v56
	v_mul_f32_e32 v52, v52, v56
	v_cvt_pk_bf16_f32 v52, v52, s0
	ds_write_b16 v51, v52 offset:50688
	v_lshlrev_b32_e32 v16, 16, v75
	v_mul_f32_e32 v20, 0xbfb8aa3b, v16
	v_exp_f32_e32 v20, v20
	v_exp_f32_e32 v22, v22
	v_add_f32_e32 v20, 1.0, v20
	v_rcp_f32_e32 v20, v20
	v_add_f32_e32 v22, 1.0, v22
	v_rcp_f32_e32 v22, v22
	v_mul_f32_e32 v16, v20, v16
	global_load_dword v20, v[48:49], off offset:64
	v_mul_f32_e32 v16, v17, v16
	v_cvt_pk_bf16_f32 v16, v16, s0
	ds_write_b16 v51, v16 offset:59664
	v_mul_f32_e32 v17, v57, v18
	v_mul_f32_e32 v21, v22, v21
	v_lshlrev_b32_e32 v16, 16, v77
	v_mul_f32_e32 v18, 0xbfb8aa3b, v16
	v_exp_f32_e32 v18, v18
	s_nop 0
	v_add_f32_e32 v18, 1.0, v18
	v_rcp_f32_e32 v18, v18
	s_nop 0
	v_mul_f32_e32 v16, v18, v16
	v_mul_f32_e32 v16, v17, v16
	v_cvt_pk_bf16_f32 v16, v16, s0
	ds_write_b16 v51, v16 offset:60192
	v_mul_f32_e32 v17, v57, v19
	v_lshlrev_b32_e32 v16, 16, v78
	v_mul_f32_e32 v18, 0xbfb8aa3b, v16
	v_exp_f32_e32 v18, v18
	s_nop 0
	v_add_f32_e32 v18, 1.0, v18
	v_rcp_f32_e32 v18, v18
	s_nop 0
	v_mul_f32_e32 v16, v18, v16
	v_mul_f32_e32 v16, v17, v16
	v_cvt_pk_bf16_f32 v16, v16, s0
	ds_write_b16 v51, v16 offset:60720
	v_mfma_f32_16x16x32_bf16 v[16:19], v[40:43], v[0:3], 0
	v_mfma_f32_16x16x32_bf16 v[16:19], v[44:47], v[4:7], v[16:19]
	s_waitcnt vmcnt(0)
	s_nop 6
	v_mul_f32_e32 v16, v20, v16
	v_mul_f32_e32 v16, v16, v21
	v_cvt_pk_bf16_f32 v16, v16, s0
	ds_write_b16 v51, v16 offset:33824
	s_nop 0
	v_mul_f32_e32 v17, v20, v17
	v_lshlrev_b32_e32 v52, 16, v76
	v_mul_f32_e32 v56, 0xbfb8aa3b, v52
	v_exp_f32_e32 v56, v56
	s_nop 0
	v_lshlrev_b32_e32 v16, 16, v79
	v_mul_f32_e32 v21, 0xbfb8aa3b, v16
	v_exp_f32_e32 v21, v21
	v_add_f32_e32 v56, 1.0, v56
	v_rcp_f32_e32 v56, v56
	v_add_f32_e32 v21, 1.0, v21
	v_rcp_f32_e32 v21, v21
	v_mul_f32_e32 v52, v56, v52
	v_mul_f32_e32 v52, v53, v52
	v_cvt_pk_bf16_f32 v52, v52, s0
	v_mul_f32_e32 v16, v21, v16
	v_mul_f32_e32 v16, v17, v16
	v_cvt_pk_bf16_f32 v16, v16, s0
	ds_write_b16 v51, v16 offset:34352
	v_mul_f32_e32 v17, v20, v18
	ds_write_b16 v51, v52 offset:51216
	v_lshlrev_b32_e32 v16, 16, v80
	v_mul_f32_e32 v18, 0xbfb8aa3b, v16
	v_exp_f32_e32 v18, v18
	s_nop 0
	v_lshlrev_b32_e32 v21, 16, v81
	v_mul_f32_e32 v53, v57, v54
	v_mul_f32_e32 v22, 0xbfb8aa3b, v21
	v_add_f32_e32 v18, 1.0, v18
	v_rcp_f32_e32 v18, v18
	v_exp_f32_e32 v22, v22
	v_mul_f32_e32 v16, v18, v16
	v_mul_f32_e32 v16, v17, v16
	v_cvt_pk_bf16_f32 v16, v16, s0
	ds_write_b16 v51, v16 offset:34880
	v_lshlrev_b32_e32 v52, 16, v82
	v_mul_f32_e32 v17, v20, v19
	v_mul_f32_e32 v54, 0xbfb8aa3b, v52
	v_exp_f32_e32 v54, v54
	s_nop 0
	v_lshlrev_b32_e32 v16, 16, v83
	v_mul_f32_e32 v18, 0xbfb8aa3b, v16
	v_exp_f32_e32 v18, v18
	v_add_f32_e32 v54, 1.0, v54
	v_add_f32_e32 v22, 1.0, v22
	v_rcp_f32_e32 v54, v54
	v_add_f32_e32 v18, 1.0, v18
	v_rcp_f32_e32 v18, v18
	v_rcp_f32_e32 v22, v22
	v_mul_f32_e32 v52, v54, v52
	v_mul_f32_e32 v52, v53, v52
	v_mul_f32_e32 v16, v18, v16
	v_mul_f32_e32 v16, v17, v16
	v_cvt_pk_bf16_f32 v16, v16, s0
	ds_write_b16 v51, v16 offset:35408
	v_mfma_f32_16x16x32_bf16 v[16:19], v[32:35], v[0:3], 0
	v_mul_f32_e32 v21, v22, v21
	v_cvt_pk_bf16_f32 v52, v52, s0
	ds_write_b16 v51, v52 offset:51744
	v_mfma_f32_16x16x32_bf16 v[16:19], v[36:39], v[4:7], v[16:19]
	s_nop 0
	v_mul_f32_e32 v53, v57, v55
	s_nop 5
	v_mul_f32_e32 v16, v20, v16
	v_mul_f32_e32 v16, v16, v21
	v_cvt_pk_bf16_f32 v16, v16, s0
	ds_write_b16 v51, v16 offset:42272
	s_nop 0
	v_mul_f32_e32 v17, v20, v17
	s_nop 0
	v_lshlrev_b32_e32 v52, 16, v84
	v_mul_f32_e32 v54, 0xbfb8aa3b, v52
	v_exp_f32_e32 v54, v54
	s_nop 0
	v_lshlrev_b32_e32 v16, 16, v85
	v_mul_f32_e32 v21, 0xbfb8aa3b, v16
	v_exp_f32_e32 v21, v21
	v_add_f32_e32 v54, 1.0, v54
	v_rcp_f32_e32 v54, v54
	v_add_f32_e32 v21, 1.0, v21
	v_rcp_f32_e32 v21, v21
	v_mul_f32_e32 v52, v54, v52
	v_mul_f32_e32 v52, v53, v52
	v_cvt_pk_bf16_f32 v52, v52, s0
	v_mul_f32_e32 v16, v21, v16
	v_mul_f32_e32 v16, v17, v16
	v_cvt_pk_bf16_f32 v16, v16, s0
	ds_write_b16 v51, v16 offset:42800
	v_mul_f32_e32 v17, v20, v18
	ds_write_b16 v51, v52 offset:52272
	v_lshlrev_b32_e32 v16, 16, v86
	v_mul_f32_e32 v18, 0xbfb8aa3b, v16
	v_exp_f32_e32 v18, v18
	s_nop 0
	v_lshlrev_b32_e32 v21, 16, v87
	v_mul_f32_e32 v22, 0xbfb8aa3b, v21
	v_exp_f32_e32 v22, v22
	v_add_f32_e32 v18, 1.0, v18
	v_rcp_f32_e32 v18, v18
	v_add_f32_e32 v22, 1.0, v22
	v_rcp_f32_e32 v22, v22
	v_mul_f32_e32 v16, v18, v16
	v_mul_f32_e32 v16, v17, v16
	v_cvt_pk_bf16_f32 v16, v16, s0
	ds_write_b16 v51, v16 offset:43328
	v_mul_f32_e32 v17, v20, v19
	v_mul_f32_e32 v21, v22, v21
	v_lshlrev_b32_e32 v16, 16, v88
	v_mul_f32_e32 v18, 0xbfb8aa3b, v16
	v_exp_f32_e32 v18, v18
	s_nop 0
	v_add_f32_e32 v18, 1.0, v18
	v_rcp_f32_e32 v18, v18
	s_nop 0
	v_mul_f32_e32 v16, v18, v16
	v_mul_f32_e32 v16, v17, v16
	v_cvt_pk_bf16_f32 v16, v16, s0
	ds_write_b16 v51, v16 offset:43856
	v_mfma_f32_16x16x32_bf16 v[16:19], v[24:27], v[0:3], 0
	v_mfma_f32_16x16x32_bf16 v[16:19], v[28:31], v[4:7], v[16:19]
	v_mfma_f32_16x16x32_bf16 v[0:3], v[8:11], v[0:3], 0
	v_mfma_f32_16x16x32_bf16 v[0:3], v[12:15], v[4:7], v[0:3]
	s_nop 5
	v_mul_f32_e32 v16, v20, v16
	v_mul_f32_e32 v16, v16, v21
	v_cvt_pk_bf16_f32 v16, v16, s0
	ds_write_b16 v51, v16 offset:50720
	s_nop 0
	s_nop 0
	v_mul_f32_e32 v17, v20, v17
	v_mul_f32_e32 v0, v20, v0
	v_mul_f32_e32 v1, v20, v1
	s_nop 0
	v_lshlrev_b32_e32 v16, 16, v89
	v_lshlrev_b32_e32 v4, 16, v90
	v_mul_f32_e32 v21, 0xbfb8aa3b, v16
	v_mul_f32_e32 v5, 0xbfb8aa3b, v4
	v_exp_f32_e32 v21, v21
	v_exp_f32_e32 v5, v5
	v_add_f32_e32 v21, 1.0, v21
	v_add_f32_e32 v5, 1.0, v5
	v_rcp_f32_e32 v21, v21
	v_rcp_f32_e32 v5, v5
	v_mul_f32_e32 v16, v21, v16
	v_mul_f32_e32 v4, v5, v4
	v_mul_f32_e32 v16, v17, v16
	v_mul_f32_e32 v0, v0, v4
	v_cvt_pk_bf16_f32 v16, v16, s0
	v_cvt_pk_bf16_f32 v0, v0, s0
	ds_write_b16 v51, v16 offset:51248
	ds_write_b16 v51, v0 offset:59168
	v_mul_f32_e32 v17, v20, v18
	v_lshlrev_b32_e32 v16, 16, v91
	v_mul_f32_e32 v18, 0xbfb8aa3b, v16
	v_lshlrev_b32_e32 v0, 16, v92
	v_mul_f32_e32 v4, 0xbfb8aa3b, v0
	v_exp_f32_e32 v18, v18
	v_exp_f32_e32 v4, v4
	v_add_f32_e32 v18, 1.0, v18
	v_add_f32_e32 v4, 1.0, v4
	v_rcp_f32_e32 v18, v18
	v_rcp_f32_e32 v4, v4
	v_mul_f32_e32 v16, v18, v16
	v_mul_f32_e32 v0, v4, v0
	v_mul_f32_e32 v16, v17, v16
	v_mul_f32_e32 v0, v1, v0
	v_cvt_pk_bf16_f32 v16, v16, s0
	v_cvt_pk_bf16_f32 v0, v0, s0
	ds_write_b16 v51, v16 offset:51776
	ds_write_b16 v51, v0 offset:59696
	v_mul_f32_e32 v1, v20, v2
	v_mul_f32_e32 v17, v20, v19
	v_lshlrev_b32_e32 v16, 16, v93
	v_mul_f32_e32 v18, 0xbfb8aa3b, v16
	v_lshlrev_b32_e32 v0, 16, v94
	v_mul_f32_e32 v2, 0xbfb8aa3b, v0
	v_exp_f32_e32 v2, v2
	v_exp_f32_e32 v18, v18
	v_add_f32_e32 v2, 1.0, v2
	v_rcp_f32_e32 v2, v2
	v_add_f32_e32 v18, 1.0, v18
	v_rcp_f32_e32 v18, v18
	v_mul_f32_e32 v0, v2, v0
	v_mul_f32_e32 v0, v1, v0
	v_cvt_pk_bf16_f32 v0, v0, s0
	ds_write_b16 v51, v0 offset:60224
	v_mul_f32_e32 v1, v20, v3
	v_mul_f32_e32 v16, v18, v16
	v_mul_f32_e32 v16, v17, v16
	v_cvt_pk_bf16_f32 v16, v16, s0
	v_lshlrev_b32_e32 v0, 16, v95
	v_mul_f32_e32 v2, 0xbfb8aa3b, v0
	v_exp_f32_e32 v2, v2
	ds_write_b16 v51, v16 offset:52304
	v_add_f32_e32 v2, 1.0, v2
	v_rcp_f32_e32 v2, v2
	s_nop 0
	v_mul_f32_e32 v0, v2, v0
	v_mul_f32_e32 v0, v1, v0
	v_cvt_pk_bf16_f32 v0, v0, s0
	ds_write_b16 v51, v0 offset:60752
	v_ashrrev_i32_e32 v0, 31, v50
	v_lshrrev_b32_e32 v0, 27, v0
	v_add_u32_e32 v0, v50, v0
	v_ashrrev_i32_e32 v2, 5, v0
	v_and_b32_e32 v0, 0xffffffe0, v0
	v_sub_u32_e32 v3, v50, v0
	v_lshlrev_b32_e32 v0, 3, v3
	v_add_u32_e32 v6, s44, v2
	v_ashrrev_i32_e32 v1, 31, v0
	v_ashrrev_i32_e32 v7, 31, v6
	v_lshl_add_u64 v[4:5], v[0:1], 1, s[26:27]
	v_lshlrev_b64 v[0:1], 11, v[6:7]
	v_lshlrev_b32_e32 v3, 4, v3
	v_lshl_add_u64 v[8:9], v[4:5], 0, v[0:1]
	v_mul_lo_u32 v0, v2, s48
	v_add3_u32 v7, 0, v3, v0
	s_waitcnt lgkmcnt(0)
	s_barrier
	ds_read_b128 v[0:3], v7 offset:33792
	ds_read_b128 v[16:19], v7 offset:42240
	ds_read_b128 v[20:23], v7 offset:50688
	ds_read_b128 v[24:27], v7 offset:59136
	s_waitcnt lgkmcnt(3)
	global_store_dwordx4 v[8:9], v[0:3], off sc1
	s_nop 1
	v_add_u32_e32 v0, 16, v6
	v_ashrrev_i32_e32 v1, 31, v0
	v_lshlrev_b64 v[0:1], 11, v[0:1]
	v_lshl_add_u64 v[8:9], v[4:5], 0, v[0:1]
	s_waitcnt lgkmcnt(2)
	global_store_dwordx4 v[8:9], v[16:19], off sc1
	s_nop 1
	v_add_u32_e32 v0, 32, v6
	v_ashrrev_i32_e32 v1, 31, v0
	v_lshlrev_b64 v[0:1], 11, v[0:1]
	v_lshl_add_u64 v[8:9], v[4:5], 0, v[0:1]
	s_waitcnt lgkmcnt(1)
	global_store_dwordx4 v[8:9], v[20:23], off sc1
	s_nop 1
	v_add_u32_e32 v0, 48, v6
	v_ashrrev_i32_e32 v1, 31, v0
	v_lshlrev_b64 v[0:1], 11, v[0:1]
	v_lshl_add_u64 v[4:5], v[4:5], 0, v[0:1]
	s_waitcnt lgkmcnt(0)
	global_store_dwordx4 v[4:5], v[24:27], off sc1
	s_nop 1
	v_mov_b32_e32 v0, v147
	s_barrier
	s_branch .LBB0_641

.LBB0_640:
	v_ashrrev_i32_e32 v0, 31, v130
	v_lshrrev_b32_e32 v0, 26, v0
	v_add_u32_e32 v0, v130, v0
	v_ashrrev_i32_e32 v6, 6, v0
	v_and_b32_e32 v0, 0xffffffc0, v0
	v_sub_u32_e32 v2, v130, v0
	v_lshlrev_b32_e32 v0, 3, v2
	v_lshlrev_b32_e32 v7, 4, v2
	v_add_u32_e32 v2, s23, v6
	v_readlane_b32 s26, v254, 58
	v_ashrrev_i32_e32 v3, 31, v2
	s_movk_i32 s5, 0x410
	v_ashrrev_i32_e32 v1, 31, v0
	v_readlane_b32 s27, v254, 59
	v_lshlrev_b64 v[4:5], 11, v[2:3]
	v_mul_lo_u32 v3, v6, s5
	v_readlane_b32 s5, v254, 39
	v_lshl_add_u64 v[0:1], v[0:1], 1, s[26:27]
	s_waitcnt lgkmcnt(0)
	v_add3_u32 v10, s5, v7, v3
	s_barrier
	v_lshl_add_u64 v[8:9], v[0:1], 0, v[4:5]
	ds_read_b128 v[4:7], v10
	ds_read_b128 v[16:19], v10 offset:8320
	ds_read_b128 v[20:23], v10 offset:16640
	ds_read_b128 v[24:27], v10 offset:24960
	ds_read_b128 v[28:31], v10 offset:33280
	ds_read_b128 v[32:35], v10 offset:41600
	ds_read_b128 v[36:39], v10 offset:49920
	ds_read_b128 v[40:43], v10 offset:58240
	s_waitcnt lgkmcnt(7)
	global_store_dwordx4 v[8:9], v[4:7], off sc1
	s_nop 1
	v_add_u32_e32 v4, 8, v2
	v_ashrrev_i32_e32 v5, 31, v4
	v_lshlrev_b64 v[4:5], 11, v[4:5]
	v_lshl_add_u64 v[8:9], v[0:1], 0, v[4:5]
	s_waitcnt lgkmcnt(6)
	global_store_dwordx4 v[8:9], v[16:19], off sc1
	s_nop 1
	v_add_u32_e32 v4, 16, v2
	v_ashrrev_i32_e32 v5, 31, v4
	v_lshlrev_b64 v[4:5], 11, v[4:5]
	v_lshl_add_u64 v[8:9], v[0:1], 0, v[4:5]
	s_waitcnt lgkmcnt(5)
	global_store_dwordx4 v[8:9], v[20:23], off sc1
	s_nop 1
	v_add_u32_e32 v4, 24, v2
	v_ashrrev_i32_e32 v5, 31, v4
	v_lshlrev_b64 v[4:5], 11, v[4:5]
	v_lshl_add_u64 v[8:9], v[0:1], 0, v[4:5]
	s_waitcnt lgkmcnt(4)
	global_store_dwordx4 v[8:9], v[24:27], off sc1
	s_nop 1
	v_add_u32_e32 v4, 32, v2
	v_ashrrev_i32_e32 v5, 31, v4
	v_lshlrev_b64 v[4:5], 11, v[4:5]
	v_lshl_add_u64 v[8:9], v[0:1], 0, v[4:5]
	s_waitcnt lgkmcnt(3)
	global_store_dwordx4 v[8:9], v[28:31], off sc1
	s_nop 1
	v_add_u32_e32 v4, 40, v2
	v_ashrrev_i32_e32 v5, 31, v4
	v_lshlrev_b64 v[4:5], 11, v[4:5]
	v_lshl_add_u64 v[8:9], v[0:1], 0, v[4:5]
	s_waitcnt lgkmcnt(2)
	global_store_dwordx4 v[8:9], v[32:35], off sc1
	s_nop 1
	v_add_u32_e32 v4, 48, v2
	v_ashrrev_i32_e32 v5, 31, v4
	v_add_u32_e32 v2, 56, v2
	v_lshlrev_b64 v[4:5], 11, v[4:5]
	v_ashrrev_i32_e32 v3, 31, v2
	v_lshl_add_u64 v[8:9], v[0:1], 0, v[4:5]
	s_waitcnt lgkmcnt(1)
	global_store_dwordx4 v[8:9], v[36:39], off sc1
	s_nop 1
	v_lshlrev_b64 v[2:3], 11, v[2:3]
	v_lshl_add_u64 v[4:5], v[0:1], 0, v[2:3]
	s_waitcnt lgkmcnt(0)
	global_store_dwordx4 v[4:5], v[40:43], off sc1
	s_nop 1
	v_mov_b32_e32 v0, v147
	s_barrier
